# hand-written prep_qkv both layers: DPP shuffles instead of ds_bpermute, precombined rope/norm constants, v_rsq, 3-row passes with next pass loads in flight (on top of win1 config)
# speedup vs baseline: 1.0028x; 1.0028x over previous
.LBB0_369:
	s_or_b64 exec, exec, s[0:1]
	s_add_u32 s0, s34, 0x100000
	s_addc_u32 s1, s35, 0
	v_writelane_b32 v250, s0, 19
	s_mov_b64 s[10:11], s[34:35]
	s_waitcnt lgkmcnt(0)
	v_writelane_b32 v250, s1, 20
	s_add_u32 s0, s34, 0x140000
	s_addc_u32 s1, s35, 0
	v_writelane_b32 v250, s0, 21
	s_barrier
	s_nop 0
	v_writelane_b32 v250, s1, 22
	s_add_u32 s14, s10, 0x5900000
	s_mov_b64 s[0:1], s[34:35]
	s_addc_u32 s15, s11, 0
	s_mov_b64 s[76:77], s[34:35]
	s_mov_b64 s[78:79], s[34:35]
	v_mov_b32_e32 v1, v0
	s_add_u32 s52, s0, 0x8f00000
	s_addc_u32 s53, s1, 0
	v_readfirstlane_b32 s0, v1
	s_ashr_i32 s12, s0, 6
	s_add_i32 s4, s12, s90
	s_mov_b64 s[8:9], 0x5900000
	s_cmpk_gt_i32 s4, 0x47ff
	s_mul_i32 s26, s94, 24
	s_mul_i32 s96, s94, 0x12000
	s_cbranch_scc1 .LBB0_394
	s_cmpk_lg_i32 s94, 0x100
	s_cbranch_scc1 qkv_orig_l0
	v_and_b32_e32 v7, 63, v0
	v_readfirstlane_b32 s12, v0
	v_lshlrev_b32_e32 v1, 4, v7
	v_and_b32_e32 v2, 31, v7
	v_and_b32_e32 v4, 15, v7
	v_lshlrev_b32_e32 v2, 4, v2
	v_lshlrev_b32_e32 v4, 4, v4
	v_add_u32_e32 v2, 0x400, v2
	v_and_b32_e32 v5, 3, v7
	v_and_b32_e32 v6, 7, v7
	v_lshlrev_b32_e32 v5, 5, v5
	v_cmp_gt_u32_e32 vcc, 4, v6
	v_lshlrev_b32_e32 v6, 5, v6
	v_cmp_gt_u32_e64 s[44:45], 16, v7
	v_cmp_lt_u32_e64 s[48:49], 15, v7
	v_cndmask_b32_e64 v8, 1.0, -1.0, vcc
	v_cmp_gt_u32_e32 vcc, 32, v7
	s_ashr_i32 s12, s12, 6
	s_add_i32 s12, s12, s90
	s_and_b64 s[48:49], s[48:49], vcc
	s_mul_i32 s3, s12, 0xc00
	s_add_u32 s4, s34, s3
	s_addc_u32 s5, s35, 0
	s_add_u32 s4, s4, 0x5900000
	s_addc_u32 s5, s5, 0
	s_lshl_b32 s3, s12, 11
	s_add_u32 s6, s34, s3
	s_addc_u32 s7, s35, 0
	s_add_u32 s6, s6, 0x8f00000
	s_addc_u32 s7, s7, 0
	s_lshl_b32 s3, s12, 8
	s_add_u32 s8, s34, s3
	s_addc_u32 s9, s35, 0
	s_add_u32 s8, s8, 0xb310000
	s_addc_u32 s9, s9, 0
	s_lshl_b32 s3, s12, 7
	s_add_u32 s0, s34, s3
	s_addc_u32 s1, s35, 0
	s_add_u32 s0, s0, 0x100000
	s_addc_u32 s1, s1, 0
	global_load_dwordx4 v[10:13], v5, s[0:1]
	global_load_dwordx4 v[14:17], v5, s[0:1] offset:16
	s_add_u32 s0, s0, 0x40000
	s_addc_u32 s1, s1, 0
	global_load_dwordx4 v[18:21], v5, s[0:1]
	global_load_dwordx4 v[22:25], v5, s[0:1] offset:16
	global_load_dwordx4 v[26:29], v6, s[38:39]
	global_load_dwordx4 v[30:33], v6, s[38:39] offset:16
	global_load_dwordx4 v[34:37], v6, s[40:41]
	global_load_dwordx4 v[38:41], v6, s[40:41] offset:16
	global_load_dwordx4 v[116:119], v1, s[4:5]
	global_load_dwordx4 v[120:123], v2, s[4:5]
	s_add_u32 s4, s4, 0x600000
	s_addc_u32 s5, s5, 0
	global_load_dwordx4 v[124:127], v1, s[4:5]
	global_load_dwordx4 v[128:131], v2, s[4:5]
	s_add_u32 s4, s4, 0x600000
	s_addc_u32 s5, s5, 0
	global_load_dwordx4 v[132:135], v1, s[4:5]
	global_load_dwordx4 v[136:139], v2, s[4:5]
	s_add_u32 s4, s4, 0x600000
	s_addc_u32 s5, s5, 0
	global_load_dwordx4 v[140:143], v1, s[4:5]
	global_load_dwordx4 v[144:147], v2, s[4:5]
	s_add_u32 s4, s4, 0x600000
	s_addc_u32 s5, s5, 0
	global_load_dwordx4 v[148:151], v1, s[4:5]
	global_load_dwordx4 v[152:155], v2, s[4:5]
	s_add_u32 s4, s4, 0x600000
	s_addc_u32 s5, s5, 0
	global_load_dwordx4 v[156:159], v1, s[4:5]
	global_load_dwordx4 v[160:163], v2, s[4:5]
	s_add_u32 s4, s4, 0x600000
	s_addc_u32 s5, s5, 0
	s_waitcnt vmcnt(12)
	v_mov_b32_dpp v42, v26 row_half_mirror row_mask:0xf bank_mask:0xf
	v_mov_b32_dpp v43, v27 row_half_mirror row_mask:0xf bank_mask:0xf
	v_mov_b32_dpp v44, v28 row_half_mirror row_mask:0xf bank_mask:0xf
	v_mov_b32_dpp v45, v29 row_half_mirror row_mask:0xf bank_mask:0xf
	v_mov_b32_dpp v46, v30 row_half_mirror row_mask:0xf bank_mask:0xf
	v_mov_b32_dpp v47, v31 row_half_mirror row_mask:0xf bank_mask:0xf
	v_mov_b32_dpp v48, v32 row_half_mirror row_mask:0xf bank_mask:0xf
	v_mov_b32_dpp v49, v33 row_half_mirror row_mask:0xf bank_mask:0xf
	v_mov_b32_dpp v50, v34 row_half_mirror row_mask:0xf bank_mask:0xf
	v_mov_b32_dpp v51, v35 row_half_mirror row_mask:0xf bank_mask:0xf
	v_mov_b32_dpp v52, v36 row_half_mirror row_mask:0xf bank_mask:0xf
	v_mov_b32_dpp v53, v37 row_half_mirror row_mask:0xf bank_mask:0xf
	v_mov_b32_dpp v54, v38 row_half_mirror row_mask:0xf bank_mask:0xf
	v_mov_b32_dpp v55, v39 row_half_mirror row_mask:0xf bank_mask:0xf
	v_mov_b32_dpp v56, v40 row_half_mirror row_mask:0xf bank_mask:0xf
	v_mov_b32_dpp v57, v41 row_half_mirror row_mask:0xf bank_mask:0xf
	v_mul_f32_e32 v100, 0x3e38aa3b, v26
	v_mul_f32_e32 v101, 0x3e38aa3b, v27
	v_mul_f32_e32 v102, 0x3e38aa3b, v28
	v_mul_f32_e32 v103, 0x3e38aa3b, v29
	v_mul_f32_e32 v104, 0x3e38aa3b, v30
	v_mul_f32_e32 v105, 0x3e38aa3b, v31
	v_mul_f32_e32 v106, 0x3e38aa3b, v32
	v_mul_f32_e32 v107, 0x3e38aa3b, v33
	v_mov_b32_dpp v42, v42 quad_perm:[3,2,1,0] row_mask:0xf bank_mask:0xf
	v_mov_b32_dpp v43, v43 quad_perm:[3,2,1,0] row_mask:0xf bank_mask:0xf
	v_mov_b32_dpp v44, v44 quad_perm:[3,2,1,0] row_mask:0xf bank_mask:0xf
	v_mov_b32_dpp v45, v45 quad_perm:[3,2,1,0] row_mask:0xf bank_mask:0xf
	v_mov_b32_dpp v46, v46 quad_perm:[3,2,1,0] row_mask:0xf bank_mask:0xf
	v_mov_b32_dpp v47, v47 quad_perm:[3,2,1,0] row_mask:0xf bank_mask:0xf
	v_mov_b32_dpp v48, v48 quad_perm:[3,2,1,0] row_mask:0xf bank_mask:0xf
	v_mov_b32_dpp v49, v49 quad_perm:[3,2,1,0] row_mask:0xf bank_mask:0xf
	v_mov_b32_dpp v50, v50 quad_perm:[3,2,1,0] row_mask:0xf bank_mask:0xf
	v_mov_b32_dpp v51, v51 quad_perm:[3,2,1,0] row_mask:0xf bank_mask:0xf
	v_mov_b32_dpp v52, v52 quad_perm:[3,2,1,0] row_mask:0xf bank_mask:0xf
	v_mov_b32_dpp v53, v53 quad_perm:[3,2,1,0] row_mask:0xf bank_mask:0xf
	v_mov_b32_dpp v54, v54 quad_perm:[3,2,1,0] row_mask:0xf bank_mask:0xf
	v_mov_b32_dpp v55, v55 quad_perm:[3,2,1,0] row_mask:0xf bank_mask:0xf
	v_mov_b32_dpp v56, v56 quad_perm:[3,2,1,0] row_mask:0xf bank_mask:0xf
	v_mov_b32_dpp v57, v57 quad_perm:[3,2,1,0] row_mask:0xf bank_mask:0xf
	v_mov_b32_e32 v108, v34
	v_mov_b32_e32 v109, v35
	v_mov_b32_e32 v110, v36
	v_mov_b32_e32 v111, v37
	v_mov_b32_e32 v112, v38
	v_mov_b32_e32 v113, v39
	v_mov_b32_e32 v114, v40
	v_mov_b32_e32 v115, v41
	v_mul_f32_e32 v58, v100, v10
	v_mul_f32_e32 v59, v101, v11
	v_mul_f32_e32 v60, v102, v12
	v_mul_f32_e32 v61, v103, v13
	v_mul_f32_e32 v62, v104, v14
	v_mul_f32_e32 v63, v105, v15
	v_mul_f32_e32 v64, v106, v16
	v_mul_f32_e32 v65, v107, v17
	v_mul_f32_e32 v74, v34, v10
	v_mul_f32_e32 v75, v35, v11
	v_mul_f32_e32 v76, v36, v12
	v_mul_f32_e32 v77, v37, v13
	v_mul_f32_e32 v78, v38, v14
	v_mul_f32_e32 v79, v39, v15
	v_mul_f32_e32 v80, v40, v16
	v_mul_f32_e32 v81, v41, v17
	v_mul_f32_e32 v18, v8, v18
	v_mul_f32_e32 v19, v8, v19
	v_mul_f32_e32 v20, v8, v20
	v_mul_f32_e32 v21, v8, v21
	v_mul_f32_e32 v22, v8, v22
	v_mul_f32_e32 v23, v8, v23
	v_mul_f32_e32 v24, v8, v24
	v_mul_f32_e32 v25, v8, v25
	v_mul_f32_e32 v66, 0x3e38aa3b, v42
	v_mul_f32_e32 v67, 0x3e38aa3b, v43
	v_mul_f32_e32 v68, 0x3e38aa3b, v44
	v_mul_f32_e32 v69, 0x3e38aa3b, v45
	v_mul_f32_e32 v70, 0x3e38aa3b, v46
	v_mul_f32_e32 v71, 0x3e38aa3b, v47
	v_mul_f32_e32 v72, 0x3e38aa3b, v48
	v_mul_f32_e32 v73, 0x3e38aa3b, v49
	v_mul_f32_e32 v82, v50, v18
	v_mul_f32_e32 v83, v51, v19
	v_mul_f32_e32 v84, v52, v20
	v_mul_f32_e32 v85, v53, v21
	v_mul_f32_e32 v86, v54, v22
	v_mul_f32_e32 v87, v55, v23
	v_mul_f32_e32 v88, v56, v24
	v_mul_f32_e32 v89, v57, v25
	v_mul_f32_e32 v66, v66, v18
	v_mul_f32_e32 v67, v67, v19
	v_mul_f32_e32 v68, v68, v20
	v_mul_f32_e32 v69, v69, v21
	v_mul_f32_e32 v70, v70, v22
	v_mul_f32_e32 v71, v71, v23
	v_mul_f32_e32 v72, v72, v24
	v_mul_f32_e32 v73, v73, v25
	s_mov_b64 s[60:61], exec
	v_mov_b32_e32 v9, 0x358637bd
	s_waitcnt vmcnt(6)
	v_lshlrev_b32_e32 v168, 16, v116
	v_and_b32_e32 v169, 0xffff0000, v116
	v_lshlrev_b32_e32 v170, 16, v117
	v_and_b32_e32 v171, 0xffff0000, v117
	v_lshlrev_b32_e32 v172, 16, v118
	v_and_b32_e32 v173, 0xffff0000, v118
	v_lshlrev_b32_e32 v174, 16, v119
	v_and_b32_e32 v175, 0xffff0000, v119
	v_lshlrev_b32_e32 v182, 16, v120
	v_and_b32_e32 v183, 0xffff0000, v120
	v_lshlrev_b32_e32 v184, 16, v121
	v_and_b32_e32 v185, 0xffff0000, v121
	v_lshlrev_b32_e32 v186, 16, v122
	v_and_b32_e32 v187, 0xffff0000, v122
	v_lshlrev_b32_e32 v188, 16, v123
	v_and_b32_e32 v189, 0xffff0000, v123
	v_lshlrev_b32_e32 v196, 16, v124
	v_and_b32_e32 v197, 0xffff0000, v124
	v_lshlrev_b32_e32 v198, 16, v125
	v_and_b32_e32 v199, 0xffff0000, v125
	v_lshlrev_b32_e32 v200, 16, v126
	v_and_b32_e32 v201, 0xffff0000, v126
	v_lshlrev_b32_e32 v202, 16, v127
	v_and_b32_e32 v203, 0xffff0000, v127
	v_lshlrev_b32_e32 v210, 16, v128
	v_and_b32_e32 v211, 0xffff0000, v128
	v_lshlrev_b32_e32 v212, 16, v129
	v_and_b32_e32 v213, 0xffff0000, v129
	v_lshlrev_b32_e32 v214, 16, v130
	v_and_b32_e32 v215, 0xffff0000, v130
	v_lshlrev_b32_e32 v216, 16, v131
	v_and_b32_e32 v217, 0xffff0000, v131
	v_lshlrev_b32_e32 v224, 16, v132
	v_and_b32_e32 v225, 0xffff0000, v132
	v_lshlrev_b32_e32 v226, 16, v133
	v_and_b32_e32 v227, 0xffff0000, v133
	v_lshlrev_b32_e32 v228, 16, v134
	v_and_b32_e32 v229, 0xffff0000, v134
	v_lshlrev_b32_e32 v230, 16, v135
	v_and_b32_e32 v231, 0xffff0000, v135
	v_lshlrev_b32_e32 v238, 16, v136
	v_and_b32_e32 v239, 0xffff0000, v136
	v_lshlrev_b32_e32 v240, 16, v137
	v_and_b32_e32 v241, 0xffff0000, v137
	v_lshlrev_b32_e32 v242, 16, v138
	v_and_b32_e32 v243, 0xffff0000, v138
	v_lshlrev_b32_e32 v244, 16, v139
	v_and_b32_e32 v245, 0xffff0000, v139
	v_mov_b32_dpp v164, v116 row_half_mirror row_mask:0xf bank_mask:0xf
	v_mov_b32_dpp v165, v117 row_half_mirror row_mask:0xf bank_mask:0xf
	v_mov_b32_dpp v166, v118 row_half_mirror row_mask:0xf bank_mask:0xf
	v_mov_b32_dpp v167, v119 row_half_mirror row_mask:0xf bank_mask:0xf
	v_mov_b32_dpp v178, v120 row_half_mirror row_mask:0xf bank_mask:0xf
	v_mov_b32_dpp v179, v121 row_half_mirror row_mask:0xf bank_mask:0xf
	v_mov_b32_dpp v180, v122 row_half_mirror row_mask:0xf bank_mask:0xf
	v_mov_b32_dpp v181, v123 row_half_mirror row_mask:0xf bank_mask:0xf
	v_mov_b32_dpp v192, v124 row_half_mirror row_mask:0xf bank_mask:0xf
	v_mov_b32_dpp v193, v125 row_half_mirror row_mask:0xf bank_mask:0xf
	v_mov_b32_dpp v194, v126 row_half_mirror row_mask:0xf bank_mask:0xf
	v_mov_b32_dpp v195, v127 row_half_mirror row_mask:0xf bank_mask:0xf
	v_mov_b32_dpp v206, v128 row_half_mirror row_mask:0xf bank_mask:0xf
	v_mov_b32_dpp v207, v129 row_half_mirror row_mask:0xf bank_mask:0xf
	v_mov_b32_dpp v208, v130 row_half_mirror row_mask:0xf bank_mask:0xf
	v_mov_b32_dpp v209, v131 row_half_mirror row_mask:0xf bank_mask:0xf
	v_mov_b32_dpp v220, v132 row_half_mirror row_mask:0xf bank_mask:0xf
	v_mov_b32_dpp v221, v133 row_half_mirror row_mask:0xf bank_mask:0xf
	v_mov_b32_dpp v222, v134 row_half_mirror row_mask:0xf bank_mask:0xf
	v_mov_b32_dpp v223, v135 row_half_mirror row_mask:0xf bank_mask:0xf
	v_mov_b32_dpp v234, v136 row_half_mirror row_mask:0xf bank_mask:0xf
	v_mov_b32_dpp v235, v137 row_half_mirror row_mask:0xf bank_mask:0xf
	v_mov_b32_dpp v236, v138 row_half_mirror row_mask:0xf bank_mask:0xf
	v_mov_b32_dpp v237, v139 row_half_mirror row_mask:0xf bank_mask:0xf
	v_mul_f32_e32 v90, v168, v168
	v_mul_f32_e32 v91, v182, v182
	v_mul_f32_e32 v92, v196, v196
	v_mul_f32_e32 v93, v210, v210
	v_mul_f32_e32 v94, v224, v224
	v_mul_f32_e32 v95, v238, v238
	v_fmac_f32_e32 v90, v169, v169
	v_fmac_f32_e32 v91, v183, v183
	v_fmac_f32_e32 v92, v197, v197
	v_fmac_f32_e32 v93, v211, v211
	v_fmac_f32_e32 v94, v225, v225
	v_fmac_f32_e32 v95, v239, v239
	v_fmac_f32_e32 v90, v170, v170
	v_fmac_f32_e32 v91, v184, v184
	v_fmac_f32_e32 v92, v198, v198
	v_fmac_f32_e32 v93, v212, v212
	v_fmac_f32_e32 v94, v226, v226
	v_fmac_f32_e32 v95, v240, v240
	v_fmac_f32_e32 v90, v171, v171
	v_fmac_f32_e32 v91, v185, v185
	v_fmac_f32_e32 v92, v199, v199
	v_fmac_f32_e32 v93, v213, v213
	v_fmac_f32_e32 v94, v227, v227
	v_fmac_f32_e32 v95, v241, v241
	v_fmac_f32_e32 v90, v172, v172
	v_fmac_f32_e32 v91, v186, v186
	v_fmac_f32_e32 v92, v200, v200
	v_fmac_f32_e32 v93, v214, v214
	v_fmac_f32_e32 v94, v228, v228
	v_fmac_f32_e32 v95, v242, v242
	v_fmac_f32_e32 v90, v173, v173
	v_fmac_f32_e32 v91, v187, v187
	v_fmac_f32_e32 v92, v201, v201
	v_fmac_f32_e32 v93, v215, v215
	v_fmac_f32_e32 v94, v229, v229
	v_fmac_f32_e32 v95, v243, v243
	v_fmac_f32_e32 v90, v174, v174
	v_fmac_f32_e32 v91, v188, v188
	v_fmac_f32_e32 v92, v202, v202
	v_fmac_f32_e32 v93, v216, v216
	v_fmac_f32_e32 v94, v230, v230
	v_fmac_f32_e32 v95, v244, v244
	v_fmac_f32_e32 v90, v175, v175
	v_fmac_f32_e32 v91, v189, v189
	v_fmac_f32_e32 v92, v203, v203
	v_fmac_f32_e32 v93, v217, v217
	v_fmac_f32_e32 v94, v231, v231
	v_fmac_f32_e32 v95, v245, v245
	v_mov_b32_dpp v164, v164 quad_perm:[3,2,1,0] row_mask:0xf bank_mask:0xf
	v_mov_b32_dpp v165, v165 quad_perm:[3,2,1,0] row_mask:0xf bank_mask:0xf
	v_mov_b32_dpp v166, v166 quad_perm:[3,2,1,0] row_mask:0xf bank_mask:0xf
	v_mov_b32_dpp v167, v167 quad_perm:[3,2,1,0] row_mask:0xf bank_mask:0xf
	v_mov_b32_dpp v178, v178 quad_perm:[3,2,1,0] row_mask:0xf bank_mask:0xf
	v_mov_b32_dpp v179, v179 quad_perm:[3,2,1,0] row_mask:0xf bank_mask:0xf
	v_mov_b32_dpp v180, v180 quad_perm:[3,2,1,0] row_mask:0xf bank_mask:0xf
	v_mov_b32_dpp v181, v181 quad_perm:[3,2,1,0] row_mask:0xf bank_mask:0xf
	v_mov_b32_dpp v192, v192 quad_perm:[3,2,1,0] row_mask:0xf bank_mask:0xf
	v_mov_b32_dpp v193, v193 quad_perm:[3,2,1,0] row_mask:0xf bank_mask:0xf
	v_mov_b32_dpp v194, v194 quad_perm:[3,2,1,0] row_mask:0xf bank_mask:0xf
	v_mov_b32_dpp v195, v195 quad_perm:[3,2,1,0] row_mask:0xf bank_mask:0xf
	v_mov_b32_dpp v206, v206 quad_perm:[3,2,1,0] row_mask:0xf bank_mask:0xf
	v_mov_b32_dpp v207, v207 quad_perm:[3,2,1,0] row_mask:0xf bank_mask:0xf
	v_mov_b32_dpp v208, v208 quad_perm:[3,2,1,0] row_mask:0xf bank_mask:0xf
	v_mov_b32_dpp v209, v209 quad_perm:[3,2,1,0] row_mask:0xf bank_mask:0xf
	v_mov_b32_dpp v220, v220 quad_perm:[3,2,1,0] row_mask:0xf bank_mask:0xf
	v_mov_b32_dpp v221, v221 quad_perm:[3,2,1,0] row_mask:0xf bank_mask:0xf
	v_mov_b32_dpp v222, v222 quad_perm:[3,2,1,0] row_mask:0xf bank_mask:0xf
	v_mov_b32_dpp v223, v223 quad_perm:[3,2,1,0] row_mask:0xf bank_mask:0xf
	v_mov_b32_dpp v234, v234 quad_perm:[3,2,1,0] row_mask:0xf bank_mask:0xf
	v_mov_b32_dpp v235, v235 quad_perm:[3,2,1,0] row_mask:0xf bank_mask:0xf
	v_mov_b32_dpp v236, v236 quad_perm:[3,2,1,0] row_mask:0xf bank_mask:0xf
	v_mov_b32_dpp v237, v237 quad_perm:[3,2,1,0] row_mask:0xf bank_mask:0xf
	v_add_f32_dpp v90, v90, v90 quad_perm:[1,0,3,2] row_mask:0xf bank_mask:0xf
	v_add_f32_dpp v91, v91, v91 quad_perm:[1,0,3,2] row_mask:0xf bank_mask:0xf
	v_add_f32_dpp v92, v92, v92 quad_perm:[1,0,3,2] row_mask:0xf bank_mask:0xf
	v_add_f32_dpp v93, v93, v93 quad_perm:[1,0,3,2] row_mask:0xf bank_mask:0xf
	v_add_f32_dpp v94, v94, v94 quad_perm:[1,0,3,2] row_mask:0xf bank_mask:0xf
	v_add_f32_dpp v95, v95, v95 quad_perm:[1,0,3,2] row_mask:0xf bank_mask:0xf
	v_add_f32_dpp v90, v90, v90 quad_perm:[2,3,0,1] row_mask:0xf bank_mask:0xf
	v_add_f32_dpp v91, v91, v91 quad_perm:[2,3,0,1] row_mask:0xf bank_mask:0xf
	v_add_f32_dpp v92, v92, v92 quad_perm:[2,3,0,1] row_mask:0xf bank_mask:0xf
	v_add_f32_dpp v93, v93, v93 quad_perm:[2,3,0,1] row_mask:0xf bank_mask:0xf
	v_add_f32_dpp v94, v94, v94 quad_perm:[2,3,0,1] row_mask:0xf bank_mask:0xf
	v_add_f32_dpp v95, v95, v95 quad_perm:[2,3,0,1] row_mask:0xf bank_mask:0xf
	v_add_f32_dpp v90, v90, v90 row_half_mirror row_mask:0xf bank_mask:0xf
	v_add_f32_dpp v91, v91, v91 row_half_mirror row_mask:0xf bank_mask:0xf
	v_add_f32_dpp v92, v92, v92 row_half_mirror row_mask:0xf bank_mask:0xf
	v_add_f32_dpp v93, v93, v93 row_half_mirror row_mask:0xf bank_mask:0xf
	v_add_f32_dpp v94, v94, v94 row_half_mirror row_mask:0xf bank_mask:0xf
	v_add_f32_dpp v95, v95, v95 row_half_mirror row_mask:0xf bank_mask:0xf
	v_fmamk_f32 v90, v90, 0x3c800000, v9
	v_fmamk_f32 v91, v91, 0x3c800000, v9
	v_fmamk_f32 v92, v92, 0x3c800000, v9
	v_fmamk_f32 v93, v93, 0x3c800000, v9
	v_fmamk_f32 v94, v94, 0x3c800000, v9
	v_fmamk_f32 v95, v95, 0x3c800000, v9
	v_rsq_f32_e32 v90, v90
	v_rsq_f32_e32 v91, v91
	v_rsq_f32_e32 v92, v92
	v_rsq_f32_e32 v93, v93
	v_rsq_f32_e32 v94, v94
	v_rsq_f32_e32 v95, v95
	v_mul_f32_e32 v168, v168, v58
	v_mul_f32_e32 v169, v169, v59
	v_mul_f32_e32 v170, v170, v60
	v_mul_f32_e32 v171, v171, v61
	v_mul_f32_e32 v172, v172, v62
	v_mul_f32_e32 v173, v173, v63
	v_mul_f32_e32 v174, v174, v64
	v_mul_f32_e32 v175, v175, v65
	v_mul_f32_e32 v182, v182, v74
	v_mul_f32_e32 v183, v183, v75
	v_mul_f32_e32 v184, v184, v76
	v_mul_f32_e32 v185, v185, v77
	v_mul_f32_e32 v186, v186, v78
	v_mul_f32_e32 v187, v187, v79
	v_mul_f32_e32 v188, v188, v80
	v_mul_f32_e32 v189, v189, v81
	v_mul_f32_e32 v196, v196, v58
	v_mul_f32_e32 v197, v197, v59
	v_mul_f32_e32 v198, v198, v60
	v_mul_f32_e32 v199, v199, v61
	v_mul_f32_e32 v200, v200, v62
	v_mul_f32_e32 v201, v201, v63
	v_mul_f32_e32 v202, v202, v64
	v_mul_f32_e32 v203, v203, v65
	v_mul_f32_e32 v210, v210, v74
	v_mul_f32_e32 v211, v211, v75
	v_mul_f32_e32 v212, v212, v76
	v_mul_f32_e32 v213, v213, v77
	v_mul_f32_e32 v214, v214, v78
	v_mul_f32_e32 v215, v215, v79
	v_mul_f32_e32 v216, v216, v80
	v_mul_f32_e32 v217, v217, v81
	v_mul_f32_e32 v224, v224, v58
	v_mul_f32_e32 v225, v225, v59
	v_mul_f32_e32 v226, v226, v60
	v_mul_f32_e32 v227, v227, v61
	v_mul_f32_e32 v228, v228, v62
	v_mul_f32_e32 v229, v229, v63
	v_mul_f32_e32 v230, v230, v64
	v_mul_f32_e32 v231, v231, v65
	v_mul_f32_e32 v238, v238, v74
	v_mul_f32_e32 v239, v239, v75
	v_mul_f32_e32 v240, v240, v76
	v_mul_f32_e32 v241, v241, v77
	v_mul_f32_e32 v242, v242, v78
	v_mul_f32_e32 v243, v243, v79
	v_mul_f32_e32 v244, v244, v80
	v_mul_f32_e32 v245, v245, v81
	v_lshlrev_b32_e32 v176, 16, v164
	v_and_b32_e32 v177, 0xffff0000, v164
	v_lshlrev_b32_e32 v190, 16, v178
	v_and_b32_e32 v191, 0xffff0000, v178
	v_lshlrev_b32_e32 v204, 16, v192
	v_and_b32_e32 v205, 0xffff0000, v192
	v_lshlrev_b32_e32 v218, 16, v206
	v_and_b32_e32 v219, 0xffff0000, v206
	v_lshlrev_b32_e32 v232, 16, v220
	v_and_b32_e32 v233, 0xffff0000, v220
	v_lshlrev_b32_e32 v246, 16, v234
	v_and_b32_e32 v247, 0xffff0000, v234
	v_fmac_f32_e32 v168, v176, v66
	v_fmac_f32_e32 v169, v177, v67
	v_fmac_f32_e32 v182, v190, v82
	v_fmac_f32_e32 v183, v191, v83
	v_fmac_f32_e32 v196, v204, v66
	v_fmac_f32_e32 v197, v205, v67
	v_fmac_f32_e32 v210, v218, v82
	v_fmac_f32_e32 v211, v219, v83
	v_fmac_f32_e32 v224, v232, v66
	v_fmac_f32_e32 v225, v233, v67
	v_fmac_f32_e32 v238, v246, v82
	v_fmac_f32_e32 v239, v247, v83
	v_lshlrev_b32_e32 v176, 16, v165
	v_and_b32_e32 v177, 0xffff0000, v165
	v_lshlrev_b32_e32 v190, 16, v179
	v_and_b32_e32 v191, 0xffff0000, v179
	v_lshlrev_b32_e32 v204, 16, v193
	v_and_b32_e32 v205, 0xffff0000, v193
	v_lshlrev_b32_e32 v218, 16, v207
	v_and_b32_e32 v219, 0xffff0000, v207
	v_lshlrev_b32_e32 v232, 16, v221
	v_and_b32_e32 v233, 0xffff0000, v221
	v_lshlrev_b32_e32 v246, 16, v235
	v_and_b32_e32 v247, 0xffff0000, v235
	v_fmac_f32_e32 v170, v176, v68
	v_fmac_f32_e32 v171, v177, v69
	v_fmac_f32_e32 v184, v190, v84
	v_fmac_f32_e32 v185, v191, v85
	v_fmac_f32_e32 v198, v204, v68
	v_fmac_f32_e32 v199, v205, v69
	v_fmac_f32_e32 v212, v218, v84
	v_fmac_f32_e32 v213, v219, v85
	v_fmac_f32_e32 v226, v232, v68
	v_fmac_f32_e32 v227, v233, v69
	v_fmac_f32_e32 v240, v246, v84
	v_fmac_f32_e32 v241, v247, v85
	v_lshlrev_b32_e32 v176, 16, v166
	v_and_b32_e32 v177, 0xffff0000, v166
	v_lshlrev_b32_e32 v190, 16, v180
	v_and_b32_e32 v191, 0xffff0000, v180
	v_lshlrev_b32_e32 v204, 16, v194
	v_and_b32_e32 v205, 0xffff0000, v194
	v_lshlrev_b32_e32 v218, 16, v208
	v_and_b32_e32 v219, 0xffff0000, v208
	v_lshlrev_b32_e32 v232, 16, v222
	v_and_b32_e32 v233, 0xffff0000, v222
	v_lshlrev_b32_e32 v246, 16, v236
	v_and_b32_e32 v247, 0xffff0000, v236
	v_fmac_f32_e32 v172, v176, v70
	v_fmac_f32_e32 v173, v177, v71
	v_fmac_f32_e32 v186, v190, v86
	v_fmac_f32_e32 v187, v191, v87
	v_fmac_f32_e32 v200, v204, v70
	v_fmac_f32_e32 v201, v205, v71
	v_fmac_f32_e32 v214, v218, v86
	v_fmac_f32_e32 v215, v219, v87
	v_fmac_f32_e32 v228, v232, v70
	v_fmac_f32_e32 v229, v233, v71
	v_fmac_f32_e32 v242, v246, v86
	v_fmac_f32_e32 v243, v247, v87
	v_lshlrev_b32_e32 v176, 16, v167
	v_and_b32_e32 v177, 0xffff0000, v167
	v_lshlrev_b32_e32 v190, 16, v181
	v_and_b32_e32 v191, 0xffff0000, v181
	v_lshlrev_b32_e32 v204, 16, v195
	v_and_b32_e32 v205, 0xffff0000, v195
	v_lshlrev_b32_e32 v218, 16, v209
	v_and_b32_e32 v219, 0xffff0000, v209
	v_lshlrev_b32_e32 v232, 16, v223
	v_and_b32_e32 v233, 0xffff0000, v223
	v_lshlrev_b32_e32 v246, 16, v237
	v_and_b32_e32 v247, 0xffff0000, v237
	v_fmac_f32_e32 v174, v176, v72
	v_fmac_f32_e32 v175, v177, v73
	v_fmac_f32_e32 v188, v190, v88
	v_fmac_f32_e32 v189, v191, v89
	v_fmac_f32_e32 v202, v204, v72
	v_fmac_f32_e32 v203, v205, v73
	v_fmac_f32_e32 v216, v218, v88
	v_fmac_f32_e32 v217, v219, v89
	v_fmac_f32_e32 v230, v232, v72
	v_fmac_f32_e32 v231, v233, v73
	v_fmac_f32_e32 v244, v246, v88
	v_fmac_f32_e32 v245, v247, v89
	v_mul_f32_e32 v168, v168, v90
	v_mul_f32_e32 v169, v169, v90
	v_mul_f32_e32 v170, v170, v90
	v_mul_f32_e32 v171, v171, v90
	v_mul_f32_e32 v172, v172, v90
	v_mul_f32_e32 v173, v173, v90
	v_mul_f32_e32 v174, v174, v90
	v_mul_f32_e32 v175, v175, v90
	v_mul_f32_e32 v182, v182, v91
	v_mul_f32_e32 v183, v183, v91
	v_mul_f32_e32 v184, v184, v91
	v_mul_f32_e32 v185, v185, v91
	v_mul_f32_e32 v186, v186, v91
	v_mul_f32_e32 v187, v187, v91
	v_mul_f32_e32 v188, v188, v91
	v_mul_f32_e32 v189, v189, v91
	v_mul_f32_e32 v196, v196, v92
	v_mul_f32_e32 v197, v197, v92
	v_mul_f32_e32 v198, v198, v92
	v_mul_f32_e32 v199, v199, v92
	v_mul_f32_e32 v200, v200, v92
	v_mul_f32_e32 v201, v201, v92
	v_mul_f32_e32 v202, v202, v92
	v_mul_f32_e32 v203, v203, v92
	v_mul_f32_e32 v210, v210, v93
	v_mul_f32_e32 v211, v211, v93
	v_mul_f32_e32 v212, v212, v93
	v_mul_f32_e32 v213, v213, v93
	v_mul_f32_e32 v214, v214, v93
	v_mul_f32_e32 v215, v215, v93
	v_mul_f32_e32 v216, v216, v93
	v_mul_f32_e32 v217, v217, v93
	v_mul_f32_e32 v224, v224, v94
	v_mul_f32_e32 v225, v225, v94
	v_mul_f32_e32 v226, v226, v94
	v_mul_f32_e32 v227, v227, v94
	v_mul_f32_e32 v228, v228, v94
	v_mul_f32_e32 v229, v229, v94
	v_mul_f32_e32 v230, v230, v94
	v_mul_f32_e32 v231, v231, v94
	v_mul_f32_e32 v238, v238, v95
	v_mul_f32_e32 v239, v239, v95
	v_mul_f32_e32 v240, v240, v95
	v_mul_f32_e32 v241, v241, v95
	v_mul_f32_e32 v242, v242, v95
	v_mul_f32_e32 v243, v243, v95
	v_mul_f32_e32 v244, v244, v95
	v_mul_f32_e32 v245, v245, v95
	v_cvt_pk_bf16_f32 v164, v168, v169
	v_cvt_pk_bf16_f32 v165, v170, v171
	v_cvt_pk_bf16_f32 v166, v172, v173
	v_cvt_pk_bf16_f32 v167, v174, v175
	v_cvt_pk_bf16_f32 v178, v182, v183
	v_cvt_pk_bf16_f32 v179, v184, v185
	v_cvt_pk_bf16_f32 v180, v186, v187
	v_cvt_pk_bf16_f32 v181, v188, v189
	v_cvt_pk_bf16_f32 v192, v196, v197
	v_cvt_pk_bf16_f32 v193, v198, v199
	v_cvt_pk_bf16_f32 v194, v200, v201
	v_cvt_pk_bf16_f32 v195, v202, v203
	v_cvt_pk_bf16_f32 v206, v210, v211
	v_cvt_pk_bf16_f32 v207, v212, v213
	v_cvt_pk_bf16_f32 v208, v214, v215
	v_cvt_pk_bf16_f32 v209, v216, v217
	v_cvt_pk_bf16_f32 v220, v224, v225
	v_cvt_pk_bf16_f32 v221, v226, v227
	v_cvt_pk_bf16_f32 v222, v228, v229
	v_cvt_pk_bf16_f32 v223, v230, v231
	v_cvt_pk_bf16_f32 v234, v238, v239
	v_cvt_pk_bf16_f32 v235, v240, v241
	v_cvt_pk_bf16_f32 v236, v242, v243
	v_cvt_pk_bf16_f32 v237, v244, v245
	s_add_u32 s22, s8, 0x480000
	s_addc_u32 s23, s9, 0
	global_store_dwordx4 v1, v[164:167], s[6:7]
	s_mov_b64 exec, s[44:45]
	global_store_dwordx4 v4, v[178:181], s[8:9]
	s_mov_b64 exec, s[48:49]
	global_store_dwordx4 v4, v[120:123], s[22:23]
	s_mov_b64 exec, s[60:61]
	s_add_u32 s6, s6, 0x400000
	s_addc_u32 s7, s7, 0
	s_add_u32 s8, s8, 0x90000
	s_addc_u32 s9, s9, 0
	s_add_u32 s22, s8, 0x480000
	s_addc_u32 s23, s9, 0
	global_store_dwordx4 v1, v[192:195], s[6:7]
	s_mov_b64 exec, s[44:45]
	global_store_dwordx4 v4, v[206:209], s[8:9]
	s_mov_b64 exec, s[48:49]
	global_store_dwordx4 v4, v[128:131], s[22:23]
	s_mov_b64 exec, s[60:61]
	s_add_u32 s6, s6, 0x400000
	s_addc_u32 s7, s7, 0
	s_add_u32 s8, s8, 0x90000
	s_addc_u32 s9, s9, 0
	s_add_u32 s22, s8, 0x480000
	s_addc_u32 s23, s9, 0
	global_store_dwordx4 v1, v[220:223], s[6:7]
	s_mov_b64 exec, s[44:45]
	global_store_dwordx4 v4, v[234:237], s[8:9]
	s_mov_b64 exec, s[48:49]
	global_store_dwordx4 v4, v[136:139], s[22:23]
	s_mov_b64 exec, s[60:61]
	s_add_u32 s6, s6, 0x400000
	s_addc_u32 s7, s7, 0
	s_add_u32 s8, s8, 0x90000
	s_addc_u32 s9, s9, 0
	global_load_dwordx4 v[116:119], v1, s[4:5]
	global_load_dwordx4 v[120:123], v2, s[4:5]
	s_add_u32 s4, s4, 0x600000
	s_addc_u32 s5, s5, 0
	global_load_dwordx4 v[124:127], v1, s[4:5]
	global_load_dwordx4 v[128:131], v2, s[4:5]
	s_add_u32 s4, s4, 0x600000
	s_addc_u32 s5, s5, 0
	global_load_dwordx4 v[132:135], v1, s[4:5]
	global_load_dwordx4 v[136:139], v2, s[4:5]
	s_add_u32 s4, s4, 0x600000
	s_addc_u32 s5, s5, 0
	s_waitcnt vmcnt(15)
	v_lshlrev_b32_e32 v168, 16, v140
	v_and_b32_e32 v169, 0xffff0000, v140
	v_lshlrev_b32_e32 v170, 16, v141
	v_and_b32_e32 v171, 0xffff0000, v141
	v_lshlrev_b32_e32 v172, 16, v142
	v_and_b32_e32 v173, 0xffff0000, v142
	v_lshlrev_b32_e32 v174, 16, v143
	v_and_b32_e32 v175, 0xffff0000, v143
	v_lshlrev_b32_e32 v182, 16, v144
	v_and_b32_e32 v183, 0xffff0000, v144
	v_lshlrev_b32_e32 v184, 16, v145
	v_and_b32_e32 v185, 0xffff0000, v145
	v_lshlrev_b32_e32 v186, 16, v146
	v_and_b32_e32 v187, 0xffff0000, v146
	v_lshlrev_b32_e32 v188, 16, v147
	v_and_b32_e32 v189, 0xffff0000, v147
	v_lshlrev_b32_e32 v196, 16, v148
	v_and_b32_e32 v197, 0xffff0000, v148
	v_lshlrev_b32_e32 v198, 16, v149
	v_and_b32_e32 v199, 0xffff0000, v149
	v_lshlrev_b32_e32 v200, 16, v150
	v_and_b32_e32 v201, 0xffff0000, v150
	v_lshlrev_b32_e32 v202, 16, v151
	v_and_b32_e32 v203, 0xffff0000, v151
	v_lshlrev_b32_e32 v210, 16, v152
	v_and_b32_e32 v211, 0xffff0000, v152
	v_lshlrev_b32_e32 v212, 16, v153
	v_and_b32_e32 v213, 0xffff0000, v153
	v_lshlrev_b32_e32 v214, 16, v154
	v_and_b32_e32 v215, 0xffff0000, v154
	v_lshlrev_b32_e32 v216, 16, v155
	v_and_b32_e32 v217, 0xffff0000, v155
	v_lshlrev_b32_e32 v224, 16, v156
	v_and_b32_e32 v225, 0xffff0000, v156
	v_lshlrev_b32_e32 v226, 16, v157
	v_and_b32_e32 v227, 0xffff0000, v157
	v_lshlrev_b32_e32 v228, 16, v158
	v_and_b32_e32 v229, 0xffff0000, v158
	v_lshlrev_b32_e32 v230, 16, v159
	v_and_b32_e32 v231, 0xffff0000, v159
	v_lshlrev_b32_e32 v238, 16, v160
	v_and_b32_e32 v239, 0xffff0000, v160
	v_lshlrev_b32_e32 v240, 16, v161
	v_and_b32_e32 v241, 0xffff0000, v161
	v_lshlrev_b32_e32 v242, 16, v162
	v_and_b32_e32 v243, 0xffff0000, v162
	v_lshlrev_b32_e32 v244, 16, v163
	v_and_b32_e32 v245, 0xffff0000, v163
	v_mov_b32_dpp v164, v140 row_half_mirror row_mask:0xf bank_mask:0xf
	v_mov_b32_dpp v165, v141 row_half_mirror row_mask:0xf bank_mask:0xf
	v_mov_b32_dpp v166, v142 row_half_mirror row_mask:0xf bank_mask:0xf
	v_mov_b32_dpp v167, v143 row_half_mirror row_mask:0xf bank_mask:0xf
	v_mov_b32_dpp v178, v144 row_half_mirror row_mask:0xf bank_mask:0xf
	v_mov_b32_dpp v179, v145 row_half_mirror row_mask:0xf bank_mask:0xf
	v_mov_b32_dpp v180, v146 row_half_mirror row_mask:0xf bank_mask:0xf
	v_mov_b32_dpp v181, v147 row_half_mirror row_mask:0xf bank_mask:0xf
	v_mov_b32_dpp v192, v148 row_half_mirror row_mask:0xf bank_mask:0xf
	v_mov_b32_dpp v193, v149 row_half_mirror row_mask:0xf bank_mask:0xf
	v_mov_b32_dpp v194, v150 row_half_mirror row_mask:0xf bank_mask:0xf
	v_mov_b32_dpp v195, v151 row_half_mirror row_mask:0xf bank_mask:0xf
	v_mov_b32_dpp v206, v152 row_half_mirror row_mask:0xf bank_mask:0xf
	v_mov_b32_dpp v207, v153 row_half_mirror row_mask:0xf bank_mask:0xf
	v_mov_b32_dpp v208, v154 row_half_mirror row_mask:0xf bank_mask:0xf
	v_mov_b32_dpp v209, v155 row_half_mirror row_mask:0xf bank_mask:0xf
	v_mov_b32_dpp v220, v156 row_half_mirror row_mask:0xf bank_mask:0xf
	v_mov_b32_dpp v221, v157 row_half_mirror row_mask:0xf bank_mask:0xf
	v_mov_b32_dpp v222, v158 row_half_mirror row_mask:0xf bank_mask:0xf
	v_mov_b32_dpp v223, v159 row_half_mirror row_mask:0xf bank_mask:0xf
	v_mov_b32_dpp v234, v160 row_half_mirror row_mask:0xf bank_mask:0xf
	v_mov_b32_dpp v235, v161 row_half_mirror row_mask:0xf bank_mask:0xf
	v_mov_b32_dpp v236, v162 row_half_mirror row_mask:0xf bank_mask:0xf
	v_mov_b32_dpp v237, v163 row_half_mirror row_mask:0xf bank_mask:0xf
	v_mul_f32_e32 v90, v168, v168
	v_mul_f32_e32 v91, v182, v182
	v_mul_f32_e32 v92, v196, v196
	v_mul_f32_e32 v93, v210, v210
	v_mul_f32_e32 v94, v224, v224
	v_mul_f32_e32 v95, v238, v238
	v_fmac_f32_e32 v90, v169, v169
	v_fmac_f32_e32 v91, v183, v183
	v_fmac_f32_e32 v92, v197, v197
	v_fmac_f32_e32 v93, v211, v211
	v_fmac_f32_e32 v94, v225, v225
	v_fmac_f32_e32 v95, v239, v239
	v_fmac_f32_e32 v90, v170, v170
	v_fmac_f32_e32 v91, v184, v184
	v_fmac_f32_e32 v92, v198, v198
	v_fmac_f32_e32 v93, v212, v212
	v_fmac_f32_e32 v94, v226, v226
	v_fmac_f32_e32 v95, v240, v240
	v_fmac_f32_e32 v90, v171, v171
	v_fmac_f32_e32 v91, v185, v185
	v_fmac_f32_e32 v92, v199, v199
	v_fmac_f32_e32 v93, v213, v213
	v_fmac_f32_e32 v94, v227, v227
	v_fmac_f32_e32 v95, v241, v241
	v_fmac_f32_e32 v90, v172, v172
	v_fmac_f32_e32 v91, v186, v186
	v_fmac_f32_e32 v92, v200, v200
	v_fmac_f32_e32 v93, v214, v214
	v_fmac_f32_e32 v94, v228, v228
	v_fmac_f32_e32 v95, v242, v242
	v_fmac_f32_e32 v90, v173, v173
	v_fmac_f32_e32 v91, v187, v187
	v_fmac_f32_e32 v92, v201, v201
	v_fmac_f32_e32 v93, v215, v215
	v_fmac_f32_e32 v94, v229, v229
	v_fmac_f32_e32 v95, v243, v243
	v_fmac_f32_e32 v90, v174, v174
	v_fmac_f32_e32 v91, v188, v188
	v_fmac_f32_e32 v92, v202, v202
	v_fmac_f32_e32 v93, v216, v216
	v_fmac_f32_e32 v94, v230, v230
	v_fmac_f32_e32 v95, v244, v244
	v_fmac_f32_e32 v90, v175, v175
	v_fmac_f32_e32 v91, v189, v189
	v_fmac_f32_e32 v92, v203, v203
	v_fmac_f32_e32 v93, v217, v217
	v_fmac_f32_e32 v94, v231, v231
	v_fmac_f32_e32 v95, v245, v245
	v_mov_b32_dpp v164, v164 quad_perm:[3,2,1,0] row_mask:0xf bank_mask:0xf
	v_mov_b32_dpp v165, v165 quad_perm:[3,2,1,0] row_mask:0xf bank_mask:0xf
	v_mov_b32_dpp v166, v166 quad_perm:[3,2,1,0] row_mask:0xf bank_mask:0xf
	v_mov_b32_dpp v167, v167 quad_perm:[3,2,1,0] row_mask:0xf bank_mask:0xf
	v_mov_b32_dpp v178, v178 quad_perm:[3,2,1,0] row_mask:0xf bank_mask:0xf
	v_mov_b32_dpp v179, v179 quad_perm:[3,2,1,0] row_mask:0xf bank_mask:0xf
	v_mov_b32_dpp v180, v180 quad_perm:[3,2,1,0] row_mask:0xf bank_mask:0xf
	v_mov_b32_dpp v181, v181 quad_perm:[3,2,1,0] row_mask:0xf bank_mask:0xf
	v_mov_b32_dpp v192, v192 quad_perm:[3,2,1,0] row_mask:0xf bank_mask:0xf
	v_mov_b32_dpp v193, v193 quad_perm:[3,2,1,0] row_mask:0xf bank_mask:0xf
	v_mov_b32_dpp v194, v194 quad_perm:[3,2,1,0] row_mask:0xf bank_mask:0xf
	v_mov_b32_dpp v195, v195 quad_perm:[3,2,1,0] row_mask:0xf bank_mask:0xf
	v_mov_b32_dpp v206, v206 quad_perm:[3,2,1,0] row_mask:0xf bank_mask:0xf
	v_mov_b32_dpp v207, v207 quad_perm:[3,2,1,0] row_mask:0xf bank_mask:0xf
	v_mov_b32_dpp v208, v208 quad_perm:[3,2,1,0] row_mask:0xf bank_mask:0xf
	v_mov_b32_dpp v209, v209 quad_perm:[3,2,1,0] row_mask:0xf bank_mask:0xf
	v_mov_b32_dpp v220, v220 quad_perm:[3,2,1,0] row_mask:0xf bank_mask:0xf
	v_mov_b32_dpp v221, v221 quad_perm:[3,2,1,0] row_mask:0xf bank_mask:0xf
	v_mov_b32_dpp v222, v222 quad_perm:[3,2,1,0] row_mask:0xf bank_mask:0xf
	v_mov_b32_dpp v223, v223 quad_perm:[3,2,1,0] row_mask:0xf bank_mask:0xf
	v_mov_b32_dpp v234, v234 quad_perm:[3,2,1,0] row_mask:0xf bank_mask:0xf
	v_mov_b32_dpp v235, v235 quad_perm:[3,2,1,0] row_mask:0xf bank_mask:0xf
	v_mov_b32_dpp v236, v236 quad_perm:[3,2,1,0] row_mask:0xf bank_mask:0xf
	v_mov_b32_dpp v237, v237 quad_perm:[3,2,1,0] row_mask:0xf bank_mask:0xf
	v_add_f32_dpp v90, v90, v90 quad_perm:[1,0,3,2] row_mask:0xf bank_mask:0xf
	v_add_f32_dpp v91, v91, v91 quad_perm:[1,0,3,2] row_mask:0xf bank_mask:0xf
	v_add_f32_dpp v92, v92, v92 quad_perm:[1,0,3,2] row_mask:0xf bank_mask:0xf
	v_add_f32_dpp v93, v93, v93 quad_perm:[1,0,3,2] row_mask:0xf bank_mask:0xf
	v_add_f32_dpp v94, v94, v94 quad_perm:[1,0,3,2] row_mask:0xf bank_mask:0xf
	v_add_f32_dpp v95, v95, v95 quad_perm:[1,0,3,2] row_mask:0xf bank_mask:0xf
	v_add_f32_dpp v90, v90, v90 quad_perm:[2,3,0,1] row_mask:0xf bank_mask:0xf
	v_add_f32_dpp v91, v91, v91 quad_perm:[2,3,0,1] row_mask:0xf bank_mask:0xf
	v_add_f32_dpp v92, v92, v92 quad_perm:[2,3,0,1] row_mask:0xf bank_mask:0xf
	v_add_f32_dpp v93, v93, v93 quad_perm:[2,3,0,1] row_mask:0xf bank_mask:0xf
	v_add_f32_dpp v94, v94, v94 quad_perm:[2,3,0,1] row_mask:0xf bank_mask:0xf
	v_add_f32_dpp v95, v95, v95 quad_perm:[2,3,0,1] row_mask:0xf bank_mask:0xf
	v_add_f32_dpp v90, v90, v90 row_half_mirror row_mask:0xf bank_mask:0xf
	v_add_f32_dpp v91, v91, v91 row_half_mirror row_mask:0xf bank_mask:0xf
	v_add_f32_dpp v92, v92, v92 row_half_mirror row_mask:0xf bank_mask:0xf
	v_add_f32_dpp v93, v93, v93 row_half_mirror row_mask:0xf bank_mask:0xf
	v_add_f32_dpp v94, v94, v94 row_half_mirror row_mask:0xf bank_mask:0xf
	v_add_f32_dpp v95, v95, v95 row_half_mirror row_mask:0xf bank_mask:0xf
	v_fmamk_f32 v90, v90, 0x3c800000, v9
	v_fmamk_f32 v91, v91, 0x3c800000, v9
	v_fmamk_f32 v92, v92, 0x3c800000, v9
	v_fmamk_f32 v93, v93, 0x3c800000, v9
	v_fmamk_f32 v94, v94, 0x3c800000, v9
	v_fmamk_f32 v95, v95, 0x3c800000, v9
	v_rsq_f32_e32 v90, v90
	v_rsq_f32_e32 v91, v91
	v_rsq_f32_e32 v92, v92
	v_rsq_f32_e32 v93, v93
	v_rsq_f32_e32 v94, v94
	v_rsq_f32_e32 v95, v95
	v_mul_f32_e32 v168, v168, v58
	v_mul_f32_e32 v169, v169, v59
	v_mul_f32_e32 v170, v170, v60
	v_mul_f32_e32 v171, v171, v61
	v_mul_f32_e32 v172, v172, v62
	v_mul_f32_e32 v173, v173, v63
	v_mul_f32_e32 v174, v174, v64
	v_mul_f32_e32 v175, v175, v65
	v_mul_f32_e32 v182, v182, v74
	v_mul_f32_e32 v183, v183, v75
	v_mul_f32_e32 v184, v184, v76
	v_mul_f32_e32 v185, v185, v77
	v_mul_f32_e32 v186, v186, v78
	v_mul_f32_e32 v187, v187, v79
	v_mul_f32_e32 v188, v188, v80
	v_mul_f32_e32 v189, v189, v81
	v_mul_f32_e32 v196, v196, v58
	v_mul_f32_e32 v197, v197, v59
	v_mul_f32_e32 v198, v198, v60
	v_mul_f32_e32 v199, v199, v61
	v_mul_f32_e32 v200, v200, v62
	v_mul_f32_e32 v201, v201, v63
	v_mul_f32_e32 v202, v202, v64
	v_mul_f32_e32 v203, v203, v65
	v_mul_f32_e32 v210, v210, v74
	v_mul_f32_e32 v211, v211, v75
	v_mul_f32_e32 v212, v212, v76
	v_mul_f32_e32 v213, v213, v77
	v_mul_f32_e32 v214, v214, v78
	v_mul_f32_e32 v215, v215, v79
	v_mul_f32_e32 v216, v216, v80
	v_mul_f32_e32 v217, v217, v81
	v_mul_f32_e32 v224, v224, v58
	v_mul_f32_e32 v225, v225, v59
	v_mul_f32_e32 v226, v226, v60
	v_mul_f32_e32 v227, v227, v61
	v_mul_f32_e32 v228, v228, v62
	v_mul_f32_e32 v229, v229, v63
	v_mul_f32_e32 v230, v230, v64
	v_mul_f32_e32 v231, v231, v65
	v_mul_f32_e32 v238, v238, v74
	v_mul_f32_e32 v239, v239, v75
	v_mul_f32_e32 v240, v240, v76
	v_mul_f32_e32 v241, v241, v77
	v_mul_f32_e32 v242, v242, v78
	v_mul_f32_e32 v243, v243, v79
	v_mul_f32_e32 v244, v244, v80
	v_mul_f32_e32 v245, v245, v81
	v_lshlrev_b32_e32 v176, 16, v164
	v_and_b32_e32 v177, 0xffff0000, v164
	v_lshlrev_b32_e32 v190, 16, v178
	v_and_b32_e32 v191, 0xffff0000, v178
	v_lshlrev_b32_e32 v204, 16, v192
	v_and_b32_e32 v205, 0xffff0000, v192
	v_lshlrev_b32_e32 v218, 16, v206
	v_and_b32_e32 v219, 0xffff0000, v206
	v_lshlrev_b32_e32 v232, 16, v220
	v_and_b32_e32 v233, 0xffff0000, v220
	v_lshlrev_b32_e32 v246, 16, v234
	v_and_b32_e32 v247, 0xffff0000, v234
	v_fmac_f32_e32 v168, v176, v66
	v_fmac_f32_e32 v169, v177, v67
	v_fmac_f32_e32 v182, v190, v82
	v_fmac_f32_e32 v183, v191, v83
	v_fmac_f32_e32 v196, v204, v66
	v_fmac_f32_e32 v197, v205, v67
	v_fmac_f32_e32 v210, v218, v82
	v_fmac_f32_e32 v211, v219, v83
	v_fmac_f32_e32 v224, v232, v66
	v_fmac_f32_e32 v225, v233, v67
	v_fmac_f32_e32 v238, v246, v82
	v_fmac_f32_e32 v239, v247, v83
	v_lshlrev_b32_e32 v176, 16, v165
	v_and_b32_e32 v177, 0xffff0000, v165
	v_lshlrev_b32_e32 v190, 16, v179
	v_and_b32_e32 v191, 0xffff0000, v179
	v_lshlrev_b32_e32 v204, 16, v193
	v_and_b32_e32 v205, 0xffff0000, v193
	v_lshlrev_b32_e32 v218, 16, v207
	v_and_b32_e32 v219, 0xffff0000, v207
	v_lshlrev_b32_e32 v232, 16, v221
	v_and_b32_e32 v233, 0xffff0000, v221
	v_lshlrev_b32_e32 v246, 16, v235
	v_and_b32_e32 v247, 0xffff0000, v235
	v_fmac_f32_e32 v170, v176, v68
	v_fmac_f32_e32 v171, v177, v69
	v_fmac_f32_e32 v184, v190, v84
	v_fmac_f32_e32 v185, v191, v85
	v_fmac_f32_e32 v198, v204, v68
	v_fmac_f32_e32 v199, v205, v69
	v_fmac_f32_e32 v212, v218, v84
	v_fmac_f32_e32 v213, v219, v85
	v_fmac_f32_e32 v226, v232, v68
	v_fmac_f32_e32 v227, v233, v69
	v_fmac_f32_e32 v240, v246, v84
	v_fmac_f32_e32 v241, v247, v85
	v_lshlrev_b32_e32 v176, 16, v166
	v_and_b32_e32 v177, 0xffff0000, v166
	v_lshlrev_b32_e32 v190, 16, v180
	v_and_b32_e32 v191, 0xffff0000, v180
	v_lshlrev_b32_e32 v204, 16, v194
	v_and_b32_e32 v205, 0xffff0000, v194
	v_lshlrev_b32_e32 v218, 16, v208
	v_and_b32_e32 v219, 0xffff0000, v208
	v_lshlrev_b32_e32 v232, 16, v222
	v_and_b32_e32 v233, 0xffff0000, v222
	v_lshlrev_b32_e32 v246, 16, v236
	v_and_b32_e32 v247, 0xffff0000, v236
	v_fmac_f32_e32 v172, v176, v70
	v_fmac_f32_e32 v173, v177, v71
	v_fmac_f32_e32 v186, v190, v86
	v_fmac_f32_e32 v187, v191, v87
	v_fmac_f32_e32 v200, v204, v70
	v_fmac_f32_e32 v201, v205, v71
	v_fmac_f32_e32 v214, v218, v86
	v_fmac_f32_e32 v215, v219, v87
	v_fmac_f32_e32 v228, v232, v70
	v_fmac_f32_e32 v229, v233, v71
	v_fmac_f32_e32 v242, v246, v86
	v_fmac_f32_e32 v243, v247, v87
	v_lshlrev_b32_e32 v176, 16, v167
	v_and_b32_e32 v177, 0xffff0000, v167
	v_lshlrev_b32_e32 v190, 16, v181
	v_and_b32_e32 v191, 0xffff0000, v181
	v_lshlrev_b32_e32 v204, 16, v195
	v_and_b32_e32 v205, 0xffff0000, v195
	v_lshlrev_b32_e32 v218, 16, v209
	v_and_b32_e32 v219, 0xffff0000, v209
	v_lshlrev_b32_e32 v232, 16, v223
	v_and_b32_e32 v233, 0xffff0000, v223
	v_lshlrev_b32_e32 v246, 16, v237
	v_and_b32_e32 v247, 0xffff0000, v237
	v_fmac_f32_e32 v174, v176, v72
	v_fmac_f32_e32 v175, v177, v73
	v_fmac_f32_e32 v188, v190, v88
	v_fmac_f32_e32 v189, v191, v89
	v_fmac_f32_e32 v202, v204, v72
	v_fmac_f32_e32 v203, v205, v73
	v_fmac_f32_e32 v216, v218, v88
	v_fmac_f32_e32 v217, v219, v89
	v_fmac_f32_e32 v230, v232, v72
	v_fmac_f32_e32 v231, v233, v73
	v_fmac_f32_e32 v244, v246, v88
	v_fmac_f32_e32 v245, v247, v89
	v_mul_f32_e32 v168, v168, v90
	v_mul_f32_e32 v169, v169, v90
	v_mul_f32_e32 v170, v170, v90
	v_mul_f32_e32 v171, v171, v90
	v_mul_f32_e32 v172, v172, v90
	v_mul_f32_e32 v173, v173, v90
	v_mul_f32_e32 v174, v174, v90
	v_mul_f32_e32 v175, v175, v90
	v_mul_f32_e32 v182, v182, v91
	v_mul_f32_e32 v183, v183, v91
	v_mul_f32_e32 v184, v184, v91
	v_mul_f32_e32 v185, v185, v91
	v_mul_f32_e32 v186, v186, v91
	v_mul_f32_e32 v187, v187, v91
	v_mul_f32_e32 v188, v188, v91
	v_mul_f32_e32 v189, v189, v91
	v_mul_f32_e32 v196, v196, v92
	v_mul_f32_e32 v197, v197, v92
	v_mul_f32_e32 v198, v198, v92
	v_mul_f32_e32 v199, v199, v92
	v_mul_f32_e32 v200, v200, v92
	v_mul_f32_e32 v201, v201, v92
	v_mul_f32_e32 v202, v202, v92
	v_mul_f32_e32 v203, v203, v92
	v_mul_f32_e32 v210, v210, v93
	v_mul_f32_e32 v211, v211, v93
	v_mul_f32_e32 v212, v212, v93
	v_mul_f32_e32 v213, v213, v93
	v_mul_f32_e32 v214, v214, v93
	v_mul_f32_e32 v215, v215, v93
	v_mul_f32_e32 v216, v216, v93
	v_mul_f32_e32 v217, v217, v93
	v_mul_f32_e32 v224, v224, v94
	v_mul_f32_e32 v225, v225, v94
	v_mul_f32_e32 v226, v226, v94
	v_mul_f32_e32 v227, v227, v94
	v_mul_f32_e32 v228, v228, v94
	v_mul_f32_e32 v229, v229, v94
	v_mul_f32_e32 v230, v230, v94
	v_mul_f32_e32 v231, v231, v94
	v_mul_f32_e32 v238, v238, v95
	v_mul_f32_e32 v239, v239, v95
	v_mul_f32_e32 v240, v240, v95
	v_mul_f32_e32 v241, v241, v95
	v_mul_f32_e32 v242, v242, v95
	v_mul_f32_e32 v243, v243, v95
	v_mul_f32_e32 v244, v244, v95
	v_mul_f32_e32 v245, v245, v95
	v_cvt_pk_bf16_f32 v164, v168, v169
	v_cvt_pk_bf16_f32 v165, v170, v171
	v_cvt_pk_bf16_f32 v166, v172, v173
	v_cvt_pk_bf16_f32 v167, v174, v175
	v_cvt_pk_bf16_f32 v178, v182, v183
	v_cvt_pk_bf16_f32 v179, v184, v185
	v_cvt_pk_bf16_f32 v180, v186, v187
	v_cvt_pk_bf16_f32 v181, v188, v189
	v_cvt_pk_bf16_f32 v192, v196, v197
	v_cvt_pk_bf16_f32 v193, v198, v199
	v_cvt_pk_bf16_f32 v194, v200, v201
	v_cvt_pk_bf16_f32 v195, v202, v203
	v_cvt_pk_bf16_f32 v206, v210, v211
	v_cvt_pk_bf16_f32 v207, v212, v213
	v_cvt_pk_bf16_f32 v208, v214, v215
	v_cvt_pk_bf16_f32 v209, v216, v217
	v_cvt_pk_bf16_f32 v220, v224, v225
	v_cvt_pk_bf16_f32 v221, v226, v227
	v_cvt_pk_bf16_f32 v222, v228, v229
	v_cvt_pk_bf16_f32 v223, v230, v231
	v_cvt_pk_bf16_f32 v234, v238, v239
	v_cvt_pk_bf16_f32 v235, v240, v241
	v_cvt_pk_bf16_f32 v236, v242, v243
	v_cvt_pk_bf16_f32 v237, v244, v245
	s_add_u32 s22, s8, 0x480000
	s_addc_u32 s23, s9, 0
	global_store_dwordx4 v1, v[164:167], s[6:7]
	s_mov_b64 exec, s[44:45]
	global_store_dwordx4 v4, v[178:181], s[8:9]
	s_mov_b64 exec, s[48:49]
	global_store_dwordx4 v4, v[144:147], s[22:23]
	s_mov_b64 exec, s[60:61]
	s_add_u32 s6, s6, 0x400000
	s_addc_u32 s7, s7, 0
	s_add_u32 s8, s8, 0x90000
	s_addc_u32 s9, s9, 0
	s_add_u32 s22, s8, 0x480000
	s_addc_u32 s23, s9, 0
	global_store_dwordx4 v1, v[192:195], s[6:7]
	s_mov_b64 exec, s[44:45]
	global_store_dwordx4 v4, v[206:209], s[8:9]
	s_mov_b64 exec, s[48:49]
	global_store_dwordx4 v4, v[152:155], s[22:23]
	s_mov_b64 exec, s[60:61]
	s_add_u32 s6, s6, 0x400000
	s_addc_u32 s7, s7, 0
	s_add_u32 s8, s8, 0x90000
	s_addc_u32 s9, s9, 0
	s_add_u32 s22, s8, 0x480000
	s_addc_u32 s23, s9, 0
	global_store_dwordx4 v1, v[220:223], s[6:7]
	s_mov_b64 exec, s[44:45]
	global_store_dwordx4 v4, v[234:237], s[8:9]
	s_mov_b64 exec, s[48:49]
	global_store_dwordx4 v4, v[160:163], s[22:23]
	s_mov_b64 exec, s[60:61]
	s_add_u32 s6, s6, 0x400000
	s_addc_u32 s7, s7, 0
	s_add_u32 s8, s8, 0x90000
	s_addc_u32 s9, s9, 0
	s_waitcnt vmcnt(9)
	v_lshlrev_b32_e32 v168, 16, v116
	v_and_b32_e32 v169, 0xffff0000, v116
	v_lshlrev_b32_e32 v170, 16, v117
	v_and_b32_e32 v171, 0xffff0000, v117
	v_lshlrev_b32_e32 v172, 16, v118
	v_and_b32_e32 v173, 0xffff0000, v118
	v_lshlrev_b32_e32 v174, 16, v119
	v_and_b32_e32 v175, 0xffff0000, v119
	v_lshlrev_b32_e32 v182, 16, v120
	v_and_b32_e32 v183, 0xffff0000, v120
	v_lshlrev_b32_e32 v184, 16, v121
	v_and_b32_e32 v185, 0xffff0000, v121
	v_lshlrev_b32_e32 v186, 16, v122
	v_and_b32_e32 v187, 0xffff0000, v122
	v_lshlrev_b32_e32 v188, 16, v123
	v_and_b32_e32 v189, 0xffff0000, v123
	v_lshlrev_b32_e32 v196, 16, v124
	v_and_b32_e32 v197, 0xffff0000, v124
	v_lshlrev_b32_e32 v198, 16, v125
	v_and_b32_e32 v199, 0xffff0000, v125
	v_lshlrev_b32_e32 v200, 16, v126
	v_and_b32_e32 v201, 0xffff0000, v126
	v_lshlrev_b32_e32 v202, 16, v127
	v_and_b32_e32 v203, 0xffff0000, v127
	v_lshlrev_b32_e32 v210, 16, v128
	v_and_b32_e32 v211, 0xffff0000, v128
	v_lshlrev_b32_e32 v212, 16, v129
	v_and_b32_e32 v213, 0xffff0000, v129
	v_lshlrev_b32_e32 v214, 16, v130
	v_and_b32_e32 v215, 0xffff0000, v130
	v_lshlrev_b32_e32 v216, 16, v131
	v_and_b32_e32 v217, 0xffff0000, v131
	v_lshlrev_b32_e32 v224, 16, v132
	v_and_b32_e32 v225, 0xffff0000, v132
	v_lshlrev_b32_e32 v226, 16, v133
	v_and_b32_e32 v227, 0xffff0000, v133
	v_lshlrev_b32_e32 v228, 16, v134
	v_and_b32_e32 v229, 0xffff0000, v134
	v_lshlrev_b32_e32 v230, 16, v135
	v_and_b32_e32 v231, 0xffff0000, v135
	v_lshlrev_b32_e32 v238, 16, v136
	v_and_b32_e32 v239, 0xffff0000, v136
	v_lshlrev_b32_e32 v240, 16, v137
	v_and_b32_e32 v241, 0xffff0000, v137
	v_lshlrev_b32_e32 v242, 16, v138
	v_and_b32_e32 v243, 0xffff0000, v138
	v_lshlrev_b32_e32 v244, 16, v139
	v_and_b32_e32 v245, 0xffff0000, v139
	v_mov_b32_dpp v164, v116 row_half_mirror row_mask:0xf bank_mask:0xf
	v_mov_b32_dpp v165, v117 row_half_mirror row_mask:0xf bank_mask:0xf
	v_mov_b32_dpp v166, v118 row_half_mirror row_mask:0xf bank_mask:0xf
	v_mov_b32_dpp v167, v119 row_half_mirror row_mask:0xf bank_mask:0xf
	v_mov_b32_dpp v178, v120 row_half_mirror row_mask:0xf bank_mask:0xf
	v_mov_b32_dpp v179, v121 row_half_mirror row_mask:0xf bank_mask:0xf
	v_mov_b32_dpp v180, v122 row_half_mirror row_mask:0xf bank_mask:0xf
	v_mov_b32_dpp v181, v123 row_half_mirror row_mask:0xf bank_mask:0xf
	v_mov_b32_dpp v192, v124 row_half_mirror row_mask:0xf bank_mask:0xf
	v_mov_b32_dpp v193, v125 row_half_mirror row_mask:0xf bank_mask:0xf
	v_mov_b32_dpp v194, v126 row_half_mirror row_mask:0xf bank_mask:0xf
	v_mov_b32_dpp v195, v127 row_half_mirror row_mask:0xf bank_mask:0xf
	v_mov_b32_dpp v206, v128 row_half_mirror row_mask:0xf bank_mask:0xf
	v_mov_b32_dpp v207, v129 row_half_mirror row_mask:0xf bank_mask:0xf
	v_mov_b32_dpp v208, v130 row_half_mirror row_mask:0xf bank_mask:0xf
	v_mov_b32_dpp v209, v131 row_half_mirror row_mask:0xf bank_mask:0xf
	v_mul_f32_e32 v90, v168, v168
	v_mul_f32_e32 v91, v182, v182
	v_mul_f32_e32 v92, v196, v196
	v_mul_f32_e32 v93, v210, v210
	v_mul_f32_e32 v94, v224, v224
	v_mul_f32_e32 v95, v238, v238
	v_fmac_f32_e32 v90, v169, v169
	v_fmac_f32_e32 v91, v183, v183
	v_fmac_f32_e32 v92, v197, v197
	v_fmac_f32_e32 v93, v211, v211
	v_fmac_f32_e32 v94, v225, v225
	v_fmac_f32_e32 v95, v239, v239
	v_fmac_f32_e32 v90, v170, v170
	v_fmac_f32_e32 v91, v184, v184
	v_fmac_f32_e32 v92, v198, v198
	v_fmac_f32_e32 v93, v212, v212
	v_fmac_f32_e32 v94, v226, v226
	v_fmac_f32_e32 v95, v240, v240
	v_fmac_f32_e32 v90, v171, v171
	v_fmac_f32_e32 v91, v185, v185
	v_fmac_f32_e32 v92, v199, v199
	v_fmac_f32_e32 v93, v213, v213
	v_fmac_f32_e32 v94, v227, v227
	v_fmac_f32_e32 v95, v241, v241
	v_fmac_f32_e32 v90, v172, v172
	v_fmac_f32_e32 v91, v186, v186
	v_fmac_f32_e32 v92, v200, v200
	v_fmac_f32_e32 v93, v214, v214
	v_fmac_f32_e32 v94, v228, v228
	v_fmac_f32_e32 v95, v242, v242
	v_fmac_f32_e32 v90, v173, v173
	v_fmac_f32_e32 v91, v187, v187
	v_fmac_f32_e32 v92, v201, v201
	v_fmac_f32_e32 v93, v215, v215
	v_fmac_f32_e32 v94, v229, v229
	v_fmac_f32_e32 v95, v243, v243
	v_fmac_f32_e32 v90, v174, v174
	v_fmac_f32_e32 v91, v188, v188
	v_fmac_f32_e32 v92, v202, v202
	v_fmac_f32_e32 v93, v216, v216
	v_fmac_f32_e32 v94, v230, v230
	v_fmac_f32_e32 v95, v244, v244
	v_fmac_f32_e32 v90, v175, v175
	v_fmac_f32_e32 v91, v189, v189
	v_fmac_f32_e32 v92, v203, v203
	v_fmac_f32_e32 v93, v217, v217
	v_fmac_f32_e32 v94, v231, v231
	v_fmac_f32_e32 v95, v245, v245
	v_mov_b32_dpp v164, v164 quad_perm:[3,2,1,0] row_mask:0xf bank_mask:0xf
	v_mov_b32_dpp v165, v165 quad_perm:[3,2,1,0] row_mask:0xf bank_mask:0xf
	v_mov_b32_dpp v166, v166 quad_perm:[3,2,1,0] row_mask:0xf bank_mask:0xf
	v_mov_b32_dpp v167, v167 quad_perm:[3,2,1,0] row_mask:0xf bank_mask:0xf
	v_mov_b32_dpp v178, v178 quad_perm:[3,2,1,0] row_mask:0xf bank_mask:0xf
	v_mov_b32_dpp v179, v179 quad_perm:[3,2,1,0] row_mask:0xf bank_mask:0xf
	v_mov_b32_dpp v180, v180 quad_perm:[3,2,1,0] row_mask:0xf bank_mask:0xf
	v_mov_b32_dpp v181, v181 quad_perm:[3,2,1,0] row_mask:0xf bank_mask:0xf
	v_mov_b32_dpp v192, v192 quad_perm:[3,2,1,0] row_mask:0xf bank_mask:0xf
	v_mov_b32_dpp v193, v193 quad_perm:[3,2,1,0] row_mask:0xf bank_mask:0xf
	v_mov_b32_dpp v194, v194 quad_perm:[3,2,1,0] row_mask:0xf bank_mask:0xf
	v_mov_b32_dpp v195, v195 quad_perm:[3,2,1,0] row_mask:0xf bank_mask:0xf
	v_mov_b32_dpp v206, v206 quad_perm:[3,2,1,0] row_mask:0xf bank_mask:0xf
	v_mov_b32_dpp v207, v207 quad_perm:[3,2,1,0] row_mask:0xf bank_mask:0xf
	v_mov_b32_dpp v208, v208 quad_perm:[3,2,1,0] row_mask:0xf bank_mask:0xf
	v_mov_b32_dpp v209, v209 quad_perm:[3,2,1,0] row_mask:0xf bank_mask:0xf
	v_add_f32_dpp v90, v90, v90 quad_perm:[1,0,3,2] row_mask:0xf bank_mask:0xf
	v_add_f32_dpp v91, v91, v91 quad_perm:[1,0,3,2] row_mask:0xf bank_mask:0xf
	v_add_f32_dpp v92, v92, v92 quad_perm:[1,0,3,2] row_mask:0xf bank_mask:0xf
	v_add_f32_dpp v93, v93, v93 quad_perm:[1,0,3,2] row_mask:0xf bank_mask:0xf
	v_add_f32_dpp v94, v94, v94 quad_perm:[1,0,3,2] row_mask:0xf bank_mask:0xf
	v_add_f32_dpp v95, v95, v95 quad_perm:[1,0,3,2] row_mask:0xf bank_mask:0xf
	v_add_f32_dpp v90, v90, v90 quad_perm:[2,3,0,1] row_mask:0xf bank_mask:0xf
	v_add_f32_dpp v91, v91, v91 quad_perm:[2,3,0,1] row_mask:0xf bank_mask:0xf
	v_add_f32_dpp v92, v92, v92 quad_perm:[2,3,0,1] row_mask:0xf bank_mask:0xf
	v_add_f32_dpp v93, v93, v93 quad_perm:[2,3,0,1] row_mask:0xf bank_mask:0xf
	v_add_f32_dpp v94, v94, v94 quad_perm:[2,3,0,1] row_mask:0xf bank_mask:0xf
	v_add_f32_dpp v95, v95, v95 quad_perm:[2,3,0,1] row_mask:0xf bank_mask:0xf
	v_add_f32_dpp v90, v90, v90 row_half_mirror row_mask:0xf bank_mask:0xf
	v_add_f32_dpp v91, v91, v91 row_half_mirror row_mask:0xf bank_mask:0xf
	v_add_f32_dpp v92, v92, v92 row_half_mirror row_mask:0xf bank_mask:0xf
	v_add_f32_dpp v93, v93, v93 row_half_mirror row_mask:0xf bank_mask:0xf
	v_add_f32_dpp v94, v94, v94 row_half_mirror row_mask:0xf bank_mask:0xf
	v_add_f32_dpp v95, v95, v95 row_half_mirror row_mask:0xf bank_mask:0xf
	v_fmamk_f32 v90, v90, 0x3c800000, v9
	v_fmamk_f32 v91, v91, 0x3c800000, v9
	v_fmamk_f32 v92, v92, 0x3c800000, v9
	v_fmamk_f32 v93, v93, 0x3c800000, v9
	v_fmamk_f32 v94, v94, 0x3c800000, v9
	v_fmamk_f32 v95, v95, 0x3c800000, v9
	v_rsq_f32_e32 v90, v90
	v_rsq_f32_e32 v91, v91
	v_rsq_f32_e32 v92, v92
	v_rsq_f32_e32 v93, v93
	v_rsq_f32_e32 v94, v94
	v_rsq_f32_e32 v95, v95
	v_mul_f32_e32 v168, v168, v58
	v_mul_f32_e32 v169, v169, v59
	v_mul_f32_e32 v170, v170, v60
	v_mul_f32_e32 v171, v171, v61
	v_mul_f32_e32 v172, v172, v62
	v_mul_f32_e32 v173, v173, v63
	v_mul_f32_e32 v174, v174, v64
	v_mul_f32_e32 v175, v175, v65
	v_mul_f32_e32 v182, v182, v74
	v_mul_f32_e32 v183, v183, v75
	v_mul_f32_e32 v184, v184, v76
	v_mul_f32_e32 v185, v185, v77
	v_mul_f32_e32 v186, v186, v78
	v_mul_f32_e32 v187, v187, v79
	v_mul_f32_e32 v188, v188, v80
	v_mul_f32_e32 v189, v189, v81
	v_mul_f32_e32 v196, v196, v58
	v_mul_f32_e32 v197, v197, v59
	v_mul_f32_e32 v198, v198, v60
	v_mul_f32_e32 v199, v199, v61
	v_mul_f32_e32 v200, v200, v62
	v_mul_f32_e32 v201, v201, v63
	v_mul_f32_e32 v202, v202, v64
	v_mul_f32_e32 v203, v203, v65
	v_mul_f32_e32 v210, v210, v74
	v_mul_f32_e32 v211, v211, v75
	v_mul_f32_e32 v212, v212, v76
	v_mul_f32_e32 v213, v213, v77
	v_mul_f32_e32 v214, v214, v78
	v_mul_f32_e32 v215, v215, v79
	v_mul_f32_e32 v216, v216, v80
	v_mul_f32_e32 v217, v217, v81
	v_mul_f32_e32 v224, v224, v100
	v_mul_f32_e32 v225, v225, v101
	v_mul_f32_e32 v226, v226, v102
	v_mul_f32_e32 v227, v227, v103
	v_mul_f32_e32 v228, v228, v104
	v_mul_f32_e32 v229, v229, v105
	v_mul_f32_e32 v230, v230, v106
	v_mul_f32_e32 v231, v231, v107
	v_mul_f32_e32 v238, v238, v108
	v_mul_f32_e32 v239, v239, v109
	v_mul_f32_e32 v240, v240, v110
	v_mul_f32_e32 v241, v241, v111
	v_mul_f32_e32 v242, v242, v112
	v_mul_f32_e32 v243, v243, v113
	v_mul_f32_e32 v244, v244, v114
	v_mul_f32_e32 v245, v245, v115
	v_lshlrev_b32_e32 v176, 16, v164
	v_and_b32_e32 v177, 0xffff0000, v164
	v_lshlrev_b32_e32 v190, 16, v178
	v_and_b32_e32 v191, 0xffff0000, v178
	v_lshlrev_b32_e32 v204, 16, v192
	v_and_b32_e32 v205, 0xffff0000, v192
	v_lshlrev_b32_e32 v218, 16, v206
	v_and_b32_e32 v219, 0xffff0000, v206
	v_fmac_f32_e32 v168, v176, v66
	v_fmac_f32_e32 v169, v177, v67
	v_fmac_f32_e32 v182, v190, v82
	v_fmac_f32_e32 v183, v191, v83
	v_fmac_f32_e32 v196, v204, v66
	v_fmac_f32_e32 v197, v205, v67
	v_fmac_f32_e32 v210, v218, v82
	v_fmac_f32_e32 v211, v219, v83
	v_lshlrev_b32_e32 v176, 16, v165
	v_and_b32_e32 v177, 0xffff0000, v165
	v_lshlrev_b32_e32 v190, 16, v179
	v_and_b32_e32 v191, 0xffff0000, v179
	v_lshlrev_b32_e32 v204, 16, v193
	v_and_b32_e32 v205, 0xffff0000, v193
	v_lshlrev_b32_e32 v218, 16, v207
	v_and_b32_e32 v219, 0xffff0000, v207
	v_fmac_f32_e32 v170, v176, v68
	v_fmac_f32_e32 v171, v177, v69
	v_fmac_f32_e32 v184, v190, v84
	v_fmac_f32_e32 v185, v191, v85
	v_fmac_f32_e32 v198, v204, v68
	v_fmac_f32_e32 v199, v205, v69
	v_fmac_f32_e32 v212, v218, v84
	v_fmac_f32_e32 v213, v219, v85
	v_lshlrev_b32_e32 v176, 16, v166
	v_and_b32_e32 v177, 0xffff0000, v166
	v_lshlrev_b32_e32 v190, 16, v180
	v_and_b32_e32 v191, 0xffff0000, v180
	v_lshlrev_b32_e32 v204, 16, v194
	v_and_b32_e32 v205, 0xffff0000, v194
	v_lshlrev_b32_e32 v218, 16, v208
	v_and_b32_e32 v219, 0xffff0000, v208
	v_fmac_f32_e32 v172, v176, v70
	v_fmac_f32_e32 v173, v177, v71
	v_fmac_f32_e32 v186, v190, v86
	v_fmac_f32_e32 v187, v191, v87
	v_fmac_f32_e32 v200, v204, v70
	v_fmac_f32_e32 v201, v205, v71
	v_fmac_f32_e32 v214, v218, v86
	v_fmac_f32_e32 v215, v219, v87
	v_lshlrev_b32_e32 v176, 16, v167
	v_and_b32_e32 v177, 0xffff0000, v167
	v_lshlrev_b32_e32 v190, 16, v181
	v_and_b32_e32 v191, 0xffff0000, v181
	v_lshlrev_b32_e32 v204, 16, v195
	v_and_b32_e32 v205, 0xffff0000, v195
	v_lshlrev_b32_e32 v218, 16, v209
	v_and_b32_e32 v219, 0xffff0000, v209
	v_fmac_f32_e32 v174, v176, v72
	v_fmac_f32_e32 v175, v177, v73
	v_fmac_f32_e32 v188, v190, v88
	v_fmac_f32_e32 v189, v191, v89
	v_fmac_f32_e32 v202, v204, v72
	v_fmac_f32_e32 v203, v205, v73
	v_fmac_f32_e32 v216, v218, v88
	v_fmac_f32_e32 v217, v219, v89
	v_mul_f32_e32 v168, v168, v90
	v_mul_f32_e32 v169, v169, v90
	v_mul_f32_e32 v170, v170, v90
	v_mul_f32_e32 v171, v171, v90
	v_mul_f32_e32 v172, v172, v90
	v_mul_f32_e32 v173, v173, v90
	v_mul_f32_e32 v174, v174, v90
	v_mul_f32_e32 v175, v175, v90
	v_mul_f32_e32 v182, v182, v91
	v_mul_f32_e32 v183, v183, v91
	v_mul_f32_e32 v184, v184, v91
	v_mul_f32_e32 v185, v185, v91
	v_mul_f32_e32 v186, v186, v91
	v_mul_f32_e32 v187, v187, v91
	v_mul_f32_e32 v188, v188, v91
	v_mul_f32_e32 v189, v189, v91
	v_mul_f32_e32 v196, v196, v92
	v_mul_f32_e32 v197, v197, v92
	v_mul_f32_e32 v198, v198, v92
	v_mul_f32_e32 v199, v199, v92
	v_mul_f32_e32 v200, v200, v92
	v_mul_f32_e32 v201, v201, v92
	v_mul_f32_e32 v202, v202, v92
	v_mul_f32_e32 v203, v203, v92
	v_mul_f32_e32 v210, v210, v93
	v_mul_f32_e32 v211, v211, v93
	v_mul_f32_e32 v212, v212, v93
	v_mul_f32_e32 v213, v213, v93
	v_mul_f32_e32 v214, v214, v93
	v_mul_f32_e32 v215, v215, v93
	v_mul_f32_e32 v216, v216, v93
	v_mul_f32_e32 v217, v217, v93
	v_mul_f32_e32 v224, v224, v94
	v_mul_f32_e32 v225, v225, v94
	v_mul_f32_e32 v226, v226, v94
	v_mul_f32_e32 v227, v227, v94
	v_mul_f32_e32 v228, v228, v94
	v_mul_f32_e32 v229, v229, v94
	v_mul_f32_e32 v230, v230, v94
	v_mul_f32_e32 v231, v231, v94
	v_mul_f32_e32 v238, v238, v95
	v_mul_f32_e32 v239, v239, v95
	v_mul_f32_e32 v240, v240, v95
	v_mul_f32_e32 v241, v241, v95
	v_mul_f32_e32 v242, v242, v95
	v_mul_f32_e32 v243, v243, v95
	v_mul_f32_e32 v244, v244, v95
	v_mul_f32_e32 v245, v245, v95
	v_cvt_pk_bf16_f32 v164, v168, v169
	v_cvt_pk_bf16_f32 v165, v170, v171
	v_cvt_pk_bf16_f32 v166, v172, v173
	v_cvt_pk_bf16_f32 v167, v174, v175
	v_cvt_pk_bf16_f32 v178, v182, v183
	v_cvt_pk_bf16_f32 v179, v184, v185
	v_cvt_pk_bf16_f32 v180, v186, v187
	v_cvt_pk_bf16_f32 v181, v188, v189
	v_cvt_pk_bf16_f32 v192, v196, v197
	v_cvt_pk_bf16_f32 v193, v198, v199
	v_cvt_pk_bf16_f32 v194, v200, v201
	v_cvt_pk_bf16_f32 v195, v202, v203
	v_cvt_pk_bf16_f32 v206, v210, v211
	v_cvt_pk_bf16_f32 v207, v212, v213
	v_cvt_pk_bf16_f32 v208, v214, v215
	v_cvt_pk_bf16_f32 v209, v216, v217
	v_cvt_pk_bf16_f32 v220, v224, v225
	v_cvt_pk_bf16_f32 v221, v226, v227
	v_cvt_pk_bf16_f32 v222, v228, v229
	v_cvt_pk_bf16_f32 v223, v230, v231
	v_cvt_pk_bf16_f32 v234, v238, v239
	v_cvt_pk_bf16_f32 v235, v240, v241
	v_cvt_pk_bf16_f32 v236, v242, v243
	v_cvt_pk_bf16_f32 v237, v244, v245
	s_add_u32 s22, s8, 0x480000
	s_addc_u32 s23, s9, 0
	global_store_dwordx4 v1, v[164:167], s[6:7]
	s_mov_b64 exec, s[44:45]
	global_store_dwordx4 v4, v[178:181], s[8:9]
	s_mov_b64 exec, s[48:49]
	global_store_dwordx4 v4, v[120:123], s[22:23]
	s_mov_b64 exec, s[60:61]
	s_add_u32 s6, s6, 0x400000
	s_addc_u32 s7, s7, 0
	s_add_u32 s8, s8, 0x90000
	s_addc_u32 s9, s9, 0
	s_add_u32 s22, s8, 0x480000
	s_addc_u32 s23, s9, 0
	global_store_dwordx4 v1, v[192:195], s[6:7]
	s_mov_b64 exec, s[44:45]
	global_store_dwordx4 v4, v[206:209], s[8:9]
	s_mov_b64 exec, s[48:49]
	global_store_dwordx4 v4, v[128:131], s[22:23]
	s_mov_b64 exec, s[60:61]
	s_add_u32 s6, s6, 0x400000
	s_addc_u32 s7, s7, 0
	s_add_u32 s8, s8, 0x90000
	s_addc_u32 s9, s9, 0
	s_lshr_b32 s0, s12, 8
	s_and_b32 s1, s12, 0xff
	s_mul_i32 s0, s0, 0x900
	s_add_i32 s0, s0, s1
	s_lshl_b32 s0, s0, 8
	s_add_u32 s8, s34, s0
	s_addc_u32 s9, s35, 0
	s_add_u32 s8, s8, 0xb300000
	s_addc_u32 s9, s9, 0
	s_add_u32 s22, s8, 0x480000
	s_addc_u32 s23, s9, 0
	global_store_dwordx4 v1, v[220:223], s[6:7]
	s_mov_b64 exec, s[44:45]
	global_store_dwordx4 v4, v[234:237], s[8:9]
	s_mov_b64 exec, s[48:49]
	global_store_dwordx4 v4, v[136:139], s[22:23]
	s_mov_b64 exec, s[60:61]
	s_branch .LBB0_394
qkv_orig_l0:
	v_and_b32_e32 v18, 7, v1
	v_lshlrev_b32_e32 v14, 5, v18
	global_load_dwordx4 v[2:5], v14, s[38:39]
	global_load_dwordx4 v[6:9], v14, s[40:41]
	global_load_dwordx4 v[10:13], v14, s[38:39] offset:16
	s_nop 0
	global_load_dwordx4 v[14:17], v14, s[40:41] offset:16
	v_lshlrev_b32_e32 v22, 5, v1
	v_readlane_b32 s60, v250, 19
	v_mov_b32_e32 v19, 0
	v_cmp_gt_u32_e32 vcc, 4, v18
	v_and_b32_e32 v18, 0x60, v22
	v_readlane_b32 s61, v250, 20
	v_mbcnt_lo_u32_b32 v23, -1, 0
	v_and_b32_e32 v21, 63, v1
	v_lshl_add_u64 v[72:73], s[60:61], 0, v[18:19]
	v_readlane_b32 s60, v250, 21
	v_mbcnt_hi_u32_b32 v25, -1, v23
	v_readlane_b32 s61, v250, 22
	s_add_i32 s44, s4, s18
	v_and_b32_e32 v1, 31, v1
	v_lshlrev_b32_e32 v20, 3, v21
	v_cmp_lt_u32_e64 s[0:1], 15, v21
	v_cmp_gt_u32_e64 s[6:7], 32, v21
	v_lshl_add_u64 v[74:75], s[60:61], 0, v[18:19]
	v_lshlrev_b32_e32 v18, 4, v21
	v_and_b32_e32 v21, 64, v25
	s_ashr_i32 s27, s26, 31
	s_ashr_i32 s45, s44, 31
	v_lshlrev_b32_e32 v22, 4, v1
	v_xor_b32_e32 v1, 1, v25
	v_add_u32_e32 v21, 64, v21
	s_lshl_b32 s5, s94, 4
	s_ashr_i32 s3, s12, 31
	s_ashr_i32 s13, s90, 31
	v_cndmask_b32_e64 v70, 1.0, -1.0, vcc
	s_lshl_b64 s[72:73], s[26:27], 11
	v_mov_b32_e32 v23, v19
	v_xor_b32_e32 v30, 2, v25
	s_lshl_b64 s[74:75], s[44:45], 11
	v_cmp_lt_i32_e32 vcc, v1, v21
	s_mov_b64 s[48:49], 0x5900400
	v_xor_b32_e32 v31, 4, v25
	v_lshl_add_u64 v[22:23], s[10:11], 0, v[22:23]
	s_add_u32 s12, s12, s90
	v_cndmask_b32_e32 v1, v25, v1, vcc
	v_cmp_lt_i32_e32 vcc, v30, v21
	v_lshl_add_u64 v[76:77], s[52:53], 0, v[18:19]
	v_lshl_add_u64 v[26:27], s[78:79], 0, v[18:19]
	v_lshl_add_u64 v[28:29], s[76:77], 0, v[18:19]
	v_lshl_add_u64 v[78:79], v[22:23], 0, s[48:49]
	v_lshl_add_u64 v[18:19], s[10:11], 0, v[18:19]
	v_cndmask_b32_e32 v22, v25, v30, vcc
	v_cmp_lt_i32_e32 vcc, v31, v21
	s_addc_u32 s13, s3, s13
	s_mov_b64 s[22:23], 0xb780000
	s_mov_b64 s[24:25], 0xb300000
	v_and_b32_e32 v24, 0xf8, v20
	v_cndmask_b32_e32 v21, v25, v31, vcc
	s_mul_hi_u32 s3, s12, 0xc00
	v_lshl_add_u64 v[84:85], v[18:19], 0, s[8:9]
	s_mul_i32 s8, s13, 0xc00
	s_mov_b32 s71, 0
	s_mul_hi_i32 s19, s26, 0xc00
	v_mov_b32_e32 v71, v70
	v_lshl_add_u64 v[80:81], v[26:27], 0, s[22:23]
	v_lshl_add_u64 v[82:83], v[28:29], 0, s[24:25]
	s_mul_i32 s76, s12, 0xc00
	v_lshlrev_b32_e32 v1, 2, v1
	v_lshlrev_b32_e32 v120, 2, v22
	v_lshlrev_b32_e32 v121, 2, v21
	s_lshl_b64 s[78:79], s[12:13], 11
	s_add_i32 s77, s3, s8
	s_movk_i32 s22, 0x7ff
	v_lshlrev_b32_e32 v122, 1, v20
	v_lshlrev_b32_e32 v123, 1, v24
	s_mov_b32 s23, 0xffff0000
	v_mov_b32_e32 v124, 0x358637bd
	s_mov_b32 s27, 0xf800000
	v_mov_b32_e32 v125, 0x260
	s_mov_b32 s80, 0x3e38aa3b
	s_movk_i32 s33, 0x7fff
	s_waitcnt vmcnt(3)
	v_mov_b32_e32 v86, v2
	v_mov_b32_e32 v87, v4
	v_mov_b32_e32 v4, v3
	s_waitcnt vmcnt(2)
	v_mov_b32_e32 v2, v6
	v_mov_b32_e32 v3, v8
	v_mov_b32_e32 v8, v7
	s_waitcnt vmcnt(1)
	v_mov_b32_e32 v6, v10
	v_mov_b32_e32 v7, v12
	v_mov_b32_e32 v12, v11
	s_waitcnt vmcnt(0)
	v_mov_b32_e32 v10, v14
	v_mov_b32_e32 v11, v16
	v_mov_b32_e32 v16, v15
	v_mov_b64_e32 v[14:15], v[76:77]
	s_branch .LBB0_373

.LBB0_1154:
	s_or_b64 exec, exec, s[0:1]
	s_mov_b64 s[6:7], s[34:35]
	s_waitcnt lgkmcnt(0)
	s_barrier
	s_add_u32 s10, s6, 0x5900000
	s_mov_b64 s[0:1], s[34:35]
	s_addc_u32 s11, s7, 0
	s_mov_b64 s[52:53], s[34:35]
	s_mov_b64 s[54:55], s[34:35]
	v_mov_b32_e32 v1, v0
	s_add_u32 s20, s0, 0x8f00000
	s_addc_u32 s21, s1, 0
	v_readfirstlane_b32 s0, v1
	s_ashr_i32 s12, s0, 6
	s_add_i32 s19, s12, s90
	s_cmpk_gt_i32 s19, 0x47ff
	s_mov_b64 s[8:9], 0x5900000
	s_cbranch_scc1 .LBB0_1179
	s_cmpk_lg_i32 s94, 0x100
	s_cbranch_scc1 qkv_orig_l1
	v_and_b32_e32 v7, 63, v0
	v_readfirstlane_b32 s12, v0
	v_lshlrev_b32_e32 v1, 4, v7
	v_and_b32_e32 v2, 31, v7
	v_and_b32_e32 v4, 15, v7
	v_lshlrev_b32_e32 v2, 4, v2
	v_lshlrev_b32_e32 v4, 4, v4
	v_add_u32_e32 v2, 0x400, v2
	v_and_b32_e32 v5, 3, v7
	v_and_b32_e32 v6, 7, v7
	v_lshlrev_b32_e32 v5, 5, v5
	v_cmp_gt_u32_e32 vcc, 4, v6
	v_lshlrev_b32_e32 v6, 5, v6
	v_cmp_gt_u32_e64 s[44:45], 16, v7
	v_cmp_lt_u32_e64 s[48:49], 15, v7
	v_cndmask_b32_e64 v8, 1.0, -1.0, vcc
	v_cmp_gt_u32_e32 vcc, 32, v7
	s_ashr_i32 s12, s12, 6
	s_add_i32 s12, s12, s90
	s_and_b64 s[48:49], s[48:49], vcc
	s_mul_i32 s3, s12, 0xc00
	s_add_u32 s4, s34, s3
	s_addc_u32 s5, s35, 0
	s_add_u32 s4, s4, 0x5900000
	s_addc_u32 s5, s5, 0
	s_lshl_b32 s3, s12, 11
	s_add_u32 s6, s34, s3
	s_addc_u32 s7, s35, 0
	s_add_u32 s6, s6, 0x8f00000
	s_addc_u32 s7, s7, 0
	s_lshl_b32 s3, s12, 8
	s_add_u32 s8, s34, s3
	s_addc_u32 s9, s35, 0
	s_add_u32 s8, s8, 0xb310000
	s_addc_u32 s9, s9, 0
	s_lshl_b32 s3, s12, 7
	s_add_u32 s0, s34, s3
	s_addc_u32 s1, s35, 0
	s_add_u32 s0, s0, 0x100000
	s_addc_u32 s1, s1, 0
	global_load_dwordx4 v[10:13], v5, s[0:1]
	global_load_dwordx4 v[14:17], v5, s[0:1] offset:16
	s_add_u32 s0, s0, 0x40000
	s_addc_u32 s1, s1, 0
	global_load_dwordx4 v[18:21], v5, s[0:1]
	global_load_dwordx4 v[22:25], v5, s[0:1] offset:16
	global_load_dwordx4 v[26:29], v6, s[38:39] offset:256
	global_load_dwordx4 v[30:33], v6, s[38:39] offset:272
	global_load_dwordx4 v[34:37], v6, s[40:41] offset:256
	global_load_dwordx4 v[38:41], v6, s[40:41] offset:272
	global_load_dwordx4 v[116:119], v1, s[4:5]
	global_load_dwordx4 v[120:123], v2, s[4:5]
	s_add_u32 s4, s4, 0x600000
	s_addc_u32 s5, s5, 0
	global_load_dwordx4 v[124:127], v1, s[4:5]
	global_load_dwordx4 v[128:131], v2, s[4:5]
	s_add_u32 s4, s4, 0x600000
	s_addc_u32 s5, s5, 0
	global_load_dwordx4 v[132:135], v1, s[4:5]
	global_load_dwordx4 v[136:139], v2, s[4:5]
	s_add_u32 s4, s4, 0x600000
	s_addc_u32 s5, s5, 0
	global_load_dwordx4 v[140:143], v1, s[4:5]
	global_load_dwordx4 v[144:147], v2, s[4:5]
	s_add_u32 s4, s4, 0x600000
	s_addc_u32 s5, s5, 0
	global_load_dwordx4 v[148:151], v1, s[4:5]
	global_load_dwordx4 v[152:155], v2, s[4:5]
	s_add_u32 s4, s4, 0x600000
	s_addc_u32 s5, s5, 0
	global_load_dwordx4 v[156:159], v1, s[4:5]
	global_load_dwordx4 v[160:163], v2, s[4:5]
	s_add_u32 s4, s4, 0x600000
	s_addc_u32 s5, s5, 0
	s_waitcnt vmcnt(12)
	v_mov_b32_dpp v42, v26 row_half_mirror row_mask:0xf bank_mask:0xf
	v_mov_b32_dpp v43, v27 row_half_mirror row_mask:0xf bank_mask:0xf
	v_mov_b32_dpp v44, v28 row_half_mirror row_mask:0xf bank_mask:0xf
	v_mov_b32_dpp v45, v29 row_half_mirror row_mask:0xf bank_mask:0xf
	v_mov_b32_dpp v46, v30 row_half_mirror row_mask:0xf bank_mask:0xf
	v_mov_b32_dpp v47, v31 row_half_mirror row_mask:0xf bank_mask:0xf
	v_mov_b32_dpp v48, v32 row_half_mirror row_mask:0xf bank_mask:0xf
	v_mov_b32_dpp v49, v33 row_half_mirror row_mask:0xf bank_mask:0xf
	v_mov_b32_dpp v50, v34 row_half_mirror row_mask:0xf bank_mask:0xf
	v_mov_b32_dpp v51, v35 row_half_mirror row_mask:0xf bank_mask:0xf
	v_mov_b32_dpp v52, v36 row_half_mirror row_mask:0xf bank_mask:0xf
	v_mov_b32_dpp v53, v37 row_half_mirror row_mask:0xf bank_mask:0xf
	v_mov_b32_dpp v54, v38 row_half_mirror row_mask:0xf bank_mask:0xf
	v_mov_b32_dpp v55, v39 row_half_mirror row_mask:0xf bank_mask:0xf
	v_mov_b32_dpp v56, v40 row_half_mirror row_mask:0xf bank_mask:0xf
	v_mov_b32_dpp v57, v41 row_half_mirror row_mask:0xf bank_mask:0xf
	v_mul_f32_e32 v100, 0x3e38aa3b, v26
	v_mul_f32_e32 v101, 0x3e38aa3b, v27
	v_mul_f32_e32 v102, 0x3e38aa3b, v28
	v_mul_f32_e32 v103, 0x3e38aa3b, v29
	v_mul_f32_e32 v104, 0x3e38aa3b, v30
	v_mul_f32_e32 v105, 0x3e38aa3b, v31
	v_mul_f32_e32 v106, 0x3e38aa3b, v32
	v_mul_f32_e32 v107, 0x3e38aa3b, v33
	v_mov_b32_dpp v42, v42 quad_perm:[3,2,1,0] row_mask:0xf bank_mask:0xf
	v_mov_b32_dpp v43, v43 quad_perm:[3,2,1,0] row_mask:0xf bank_mask:0xf
	v_mov_b32_dpp v44, v44 quad_perm:[3,2,1,0] row_mask:0xf bank_mask:0xf
	v_mov_b32_dpp v45, v45 quad_perm:[3,2,1,0] row_mask:0xf bank_mask:0xf
	v_mov_b32_dpp v46, v46 quad_perm:[3,2,1,0] row_mask:0xf bank_mask:0xf
	v_mov_b32_dpp v47, v47 quad_perm:[3,2,1,0] row_mask:0xf bank_mask:0xf
	v_mov_b32_dpp v48, v48 quad_perm:[3,2,1,0] row_mask:0xf bank_mask:0xf
	v_mov_b32_dpp v49, v49 quad_perm:[3,2,1,0] row_mask:0xf bank_mask:0xf
	v_mov_b32_dpp v50, v50 quad_perm:[3,2,1,0] row_mask:0xf bank_mask:0xf
	v_mov_b32_dpp v51, v51 quad_perm:[3,2,1,0] row_mask:0xf bank_mask:0xf
	v_mov_b32_dpp v52, v52 quad_perm:[3,2,1,0] row_mask:0xf bank_mask:0xf
	v_mov_b32_dpp v53, v53 quad_perm:[3,2,1,0] row_mask:0xf bank_mask:0xf
	v_mov_b32_dpp v54, v54 quad_perm:[3,2,1,0] row_mask:0xf bank_mask:0xf
	v_mov_b32_dpp v55, v55 quad_perm:[3,2,1,0] row_mask:0xf bank_mask:0xf
	v_mov_b32_dpp v56, v56 quad_perm:[3,2,1,0] row_mask:0xf bank_mask:0xf
	v_mov_b32_dpp v57, v57 quad_perm:[3,2,1,0] row_mask:0xf bank_mask:0xf
	v_mov_b32_e32 v108, v34
	v_mov_b32_e32 v109, v35
	v_mov_b32_e32 v110, v36
	v_mov_b32_e32 v111, v37
	v_mov_b32_e32 v112, v38
	v_mov_b32_e32 v113, v39
	v_mov_b32_e32 v114, v40
	v_mov_b32_e32 v115, v41
	v_mul_f32_e32 v58, v100, v10
	v_mul_f32_e32 v59, v101, v11
	v_mul_f32_e32 v60, v102, v12
	v_mul_f32_e32 v61, v103, v13
	v_mul_f32_e32 v62, v104, v14
	v_mul_f32_e32 v63, v105, v15
	v_mul_f32_e32 v64, v106, v16
	v_mul_f32_e32 v65, v107, v17
	v_mul_f32_e32 v74, v34, v10
	v_mul_f32_e32 v75, v35, v11
	v_mul_f32_e32 v76, v36, v12
	v_mul_f32_e32 v77, v37, v13
	v_mul_f32_e32 v78, v38, v14
	v_mul_f32_e32 v79, v39, v15
	v_mul_f32_e32 v80, v40, v16
	v_mul_f32_e32 v81, v41, v17
	v_mul_f32_e32 v18, v8, v18
	v_mul_f32_e32 v19, v8, v19
	v_mul_f32_e32 v20, v8, v20
	v_mul_f32_e32 v21, v8, v21
	v_mul_f32_e32 v22, v8, v22
	v_mul_f32_e32 v23, v8, v23
	v_mul_f32_e32 v24, v8, v24
	v_mul_f32_e32 v25, v8, v25
	v_mul_f32_e32 v66, 0x3e38aa3b, v42
	v_mul_f32_e32 v67, 0x3e38aa3b, v43
	v_mul_f32_e32 v68, 0x3e38aa3b, v44
	v_mul_f32_e32 v69, 0x3e38aa3b, v45
	v_mul_f32_e32 v70, 0x3e38aa3b, v46
	v_mul_f32_e32 v71, 0x3e38aa3b, v47
	v_mul_f32_e32 v72, 0x3e38aa3b, v48
	v_mul_f32_e32 v73, 0x3e38aa3b, v49
	v_mul_f32_e32 v82, v50, v18
	v_mul_f32_e32 v83, v51, v19
	v_mul_f32_e32 v84, v52, v20
	v_mul_f32_e32 v85, v53, v21
	v_mul_f32_e32 v86, v54, v22
	v_mul_f32_e32 v87, v55, v23
	v_mul_f32_e32 v88, v56, v24
	v_mul_f32_e32 v89, v57, v25
	v_mul_f32_e32 v66, v66, v18
	v_mul_f32_e32 v67, v67, v19
	v_mul_f32_e32 v68, v68, v20
	v_mul_f32_e32 v69, v69, v21
	v_mul_f32_e32 v70, v70, v22
	v_mul_f32_e32 v71, v71, v23
	v_mul_f32_e32 v72, v72, v24
	v_mul_f32_e32 v73, v73, v25
	s_mov_b64 s[60:61], exec
	v_mov_b32_e32 v9, 0x358637bd
	s_waitcnt vmcnt(6)
	v_lshlrev_b32_e32 v168, 16, v116
	v_and_b32_e32 v169, 0xffff0000, v116
	v_lshlrev_b32_e32 v170, 16, v117
	v_and_b32_e32 v171, 0xffff0000, v117
	v_lshlrev_b32_e32 v172, 16, v118
	v_and_b32_e32 v173, 0xffff0000, v118
	v_lshlrev_b32_e32 v174, 16, v119
	v_and_b32_e32 v175, 0xffff0000, v119
	v_lshlrev_b32_e32 v182, 16, v120
	v_and_b32_e32 v183, 0xffff0000, v120
	v_lshlrev_b32_e32 v184, 16, v121
	v_and_b32_e32 v185, 0xffff0000, v121
	v_lshlrev_b32_e32 v186, 16, v122
	v_and_b32_e32 v187, 0xffff0000, v122
	v_lshlrev_b32_e32 v188, 16, v123
	v_and_b32_e32 v189, 0xffff0000, v123
	v_lshlrev_b32_e32 v196, 16, v124
	v_and_b32_e32 v197, 0xffff0000, v124
	v_lshlrev_b32_e32 v198, 16, v125
	v_and_b32_e32 v199, 0xffff0000, v125
	v_lshlrev_b32_e32 v200, 16, v126
	v_and_b32_e32 v201, 0xffff0000, v126
	v_lshlrev_b32_e32 v202, 16, v127
	v_and_b32_e32 v203, 0xffff0000, v127
	v_lshlrev_b32_e32 v210, 16, v128
	v_and_b32_e32 v211, 0xffff0000, v128
	v_lshlrev_b32_e32 v212, 16, v129
	v_and_b32_e32 v213, 0xffff0000, v129
	v_lshlrev_b32_e32 v214, 16, v130
	v_and_b32_e32 v215, 0xffff0000, v130
	v_lshlrev_b32_e32 v216, 16, v131
	v_and_b32_e32 v217, 0xffff0000, v131
	v_lshlrev_b32_e32 v224, 16, v132
	v_and_b32_e32 v225, 0xffff0000, v132
	v_lshlrev_b32_e32 v226, 16, v133
	v_and_b32_e32 v227, 0xffff0000, v133
	v_lshlrev_b32_e32 v228, 16, v134
	v_and_b32_e32 v229, 0xffff0000, v134
	v_lshlrev_b32_e32 v230, 16, v135
	v_and_b32_e32 v231, 0xffff0000, v135
	v_lshlrev_b32_e32 v238, 16, v136
	v_and_b32_e32 v239, 0xffff0000, v136
	v_lshlrev_b32_e32 v240, 16, v137
	v_and_b32_e32 v241, 0xffff0000, v137
	v_lshlrev_b32_e32 v242, 16, v138
	v_and_b32_e32 v243, 0xffff0000, v138
	v_lshlrev_b32_e32 v244, 16, v139
	v_and_b32_e32 v245, 0xffff0000, v139
	v_mov_b32_dpp v164, v116 row_half_mirror row_mask:0xf bank_mask:0xf
	v_mov_b32_dpp v165, v117 row_half_mirror row_mask:0xf bank_mask:0xf
	v_mov_b32_dpp v166, v118 row_half_mirror row_mask:0xf bank_mask:0xf
	v_mov_b32_dpp v167, v119 row_half_mirror row_mask:0xf bank_mask:0xf
	v_mov_b32_dpp v178, v120 row_half_mirror row_mask:0xf bank_mask:0xf
	v_mov_b32_dpp v179, v121 row_half_mirror row_mask:0xf bank_mask:0xf
	v_mov_b32_dpp v180, v122 row_half_mirror row_mask:0xf bank_mask:0xf
	v_mov_b32_dpp v181, v123 row_half_mirror row_mask:0xf bank_mask:0xf
	v_mov_b32_dpp v192, v124 row_half_mirror row_mask:0xf bank_mask:0xf
	v_mov_b32_dpp v193, v125 row_half_mirror row_mask:0xf bank_mask:0xf
	v_mov_b32_dpp v194, v126 row_half_mirror row_mask:0xf bank_mask:0xf
	v_mov_b32_dpp v195, v127 row_half_mirror row_mask:0xf bank_mask:0xf
	v_mov_b32_dpp v206, v128 row_half_mirror row_mask:0xf bank_mask:0xf
	v_mov_b32_dpp v207, v129 row_half_mirror row_mask:0xf bank_mask:0xf
	v_mov_b32_dpp v208, v130 row_half_mirror row_mask:0xf bank_mask:0xf
	v_mov_b32_dpp v209, v131 row_half_mirror row_mask:0xf bank_mask:0xf
	v_mov_b32_dpp v220, v132 row_half_mirror row_mask:0xf bank_mask:0xf
	v_mov_b32_dpp v221, v133 row_half_mirror row_mask:0xf bank_mask:0xf
	v_mov_b32_dpp v222, v134 row_half_mirror row_mask:0xf bank_mask:0xf
	v_mov_b32_dpp v223, v135 row_half_mirror row_mask:0xf bank_mask:0xf
	v_mov_b32_dpp v234, v136 row_half_mirror row_mask:0xf bank_mask:0xf
	v_mov_b32_dpp v235, v137 row_half_mirror row_mask:0xf bank_mask:0xf
	v_mov_b32_dpp v236, v138 row_half_mirror row_mask:0xf bank_mask:0xf
	v_mov_b32_dpp v237, v139 row_half_mirror row_mask:0xf bank_mask:0xf
	v_mul_f32_e32 v90, v168, v168
	v_mul_f32_e32 v91, v182, v182
	v_mul_f32_e32 v92, v196, v196
	v_mul_f32_e32 v93, v210, v210
	v_mul_f32_e32 v94, v224, v224
	v_mul_f32_e32 v95, v238, v238
	v_fmac_f32_e32 v90, v169, v169
	v_fmac_f32_e32 v91, v183, v183
	v_fmac_f32_e32 v92, v197, v197
	v_fmac_f32_e32 v93, v211, v211
	v_fmac_f32_e32 v94, v225, v225
	v_fmac_f32_e32 v95, v239, v239
	v_fmac_f32_e32 v90, v170, v170
	v_fmac_f32_e32 v91, v184, v184
	v_fmac_f32_e32 v92, v198, v198
	v_fmac_f32_e32 v93, v212, v212
	v_fmac_f32_e32 v94, v226, v226
	v_fmac_f32_e32 v95, v240, v240
	v_fmac_f32_e32 v90, v171, v171
	v_fmac_f32_e32 v91, v185, v185
	v_fmac_f32_e32 v92, v199, v199
	v_fmac_f32_e32 v93, v213, v213
	v_fmac_f32_e32 v94, v227, v227
	v_fmac_f32_e32 v95, v241, v241
	v_fmac_f32_e32 v90, v172, v172
	v_fmac_f32_e32 v91, v186, v186
	v_fmac_f32_e32 v92, v200, v200
	v_fmac_f32_e32 v93, v214, v214
	v_fmac_f32_e32 v94, v228, v228
	v_fmac_f32_e32 v95, v242, v242
	v_fmac_f32_e32 v90, v173, v173
	v_fmac_f32_e32 v91, v187, v187
	v_fmac_f32_e32 v92, v201, v201
	v_fmac_f32_e32 v93, v215, v215
	v_fmac_f32_e32 v94, v229, v229
	v_fmac_f32_e32 v95, v243, v243
	v_fmac_f32_e32 v90, v174, v174
	v_fmac_f32_e32 v91, v188, v188
	v_fmac_f32_e32 v92, v202, v202
	v_fmac_f32_e32 v93, v216, v216
	v_fmac_f32_e32 v94, v230, v230
	v_fmac_f32_e32 v95, v244, v244
	v_fmac_f32_e32 v90, v175, v175
	v_fmac_f32_e32 v91, v189, v189
	v_fmac_f32_e32 v92, v203, v203
	v_fmac_f32_e32 v93, v217, v217
	v_fmac_f32_e32 v94, v231, v231
	v_fmac_f32_e32 v95, v245, v245
	v_mov_b32_dpp v164, v164 quad_perm:[3,2,1,0] row_mask:0xf bank_mask:0xf
	v_mov_b32_dpp v165, v165 quad_perm:[3,2,1,0] row_mask:0xf bank_mask:0xf
	v_mov_b32_dpp v166, v166 quad_perm:[3,2,1,0] row_mask:0xf bank_mask:0xf
	v_mov_b32_dpp v167, v167 quad_perm:[3,2,1,0] row_mask:0xf bank_mask:0xf
	v_mov_b32_dpp v178, v178 quad_perm:[3,2,1,0] row_mask:0xf bank_mask:0xf
	v_mov_b32_dpp v179, v179 quad_perm:[3,2,1,0] row_mask:0xf bank_mask:0xf
	v_mov_b32_dpp v180, v180 quad_perm:[3,2,1,0] row_mask:0xf bank_mask:0xf
	v_mov_b32_dpp v181, v181 quad_perm:[3,2,1,0] row_mask:0xf bank_mask:0xf
	v_mov_b32_dpp v192, v192 quad_perm:[3,2,1,0] row_mask:0xf bank_mask:0xf
	v_mov_b32_dpp v193, v193 quad_perm:[3,2,1,0] row_mask:0xf bank_mask:0xf
	v_mov_b32_dpp v194, v194 quad_perm:[3,2,1,0] row_mask:0xf bank_mask:0xf
	v_mov_b32_dpp v195, v195 quad_perm:[3,2,1,0] row_mask:0xf bank_mask:0xf
	v_mov_b32_dpp v206, v206 quad_perm:[3,2,1,0] row_mask:0xf bank_mask:0xf
	v_mov_b32_dpp v207, v207 quad_perm:[3,2,1,0] row_mask:0xf bank_mask:0xf
	v_mov_b32_dpp v208, v208 quad_perm:[3,2,1,0] row_mask:0xf bank_mask:0xf
	v_mov_b32_dpp v209, v209 quad_perm:[3,2,1,0] row_mask:0xf bank_mask:0xf
	v_mov_b32_dpp v220, v220 quad_perm:[3,2,1,0] row_mask:0xf bank_mask:0xf
	v_mov_b32_dpp v221, v221 quad_perm:[3,2,1,0] row_mask:0xf bank_mask:0xf
	v_mov_b32_dpp v222, v222 quad_perm:[3,2,1,0] row_mask:0xf bank_mask:0xf
	v_mov_b32_dpp v223, v223 quad_perm:[3,2,1,0] row_mask:0xf bank_mask:0xf
	v_mov_b32_dpp v234, v234 quad_perm:[3,2,1,0] row_mask:0xf bank_mask:0xf
	v_mov_b32_dpp v235, v235 quad_perm:[3,2,1,0] row_mask:0xf bank_mask:0xf
	v_mov_b32_dpp v236, v236 quad_perm:[3,2,1,0] row_mask:0xf bank_mask:0xf
	v_mov_b32_dpp v237, v237 quad_perm:[3,2,1,0] row_mask:0xf bank_mask:0xf
	v_add_f32_dpp v90, v90, v90 quad_perm:[1,0,3,2] row_mask:0xf bank_mask:0xf
	v_add_f32_dpp v91, v91, v91 quad_perm:[1,0,3,2] row_mask:0xf bank_mask:0xf
	v_add_f32_dpp v92, v92, v92 quad_perm:[1,0,3,2] row_mask:0xf bank_mask:0xf
	v_add_f32_dpp v93, v93, v93 quad_perm:[1,0,3,2] row_mask:0xf bank_mask:0xf
	v_add_f32_dpp v94, v94, v94 quad_perm:[1,0,3,2] row_mask:0xf bank_mask:0xf
	v_add_f32_dpp v95, v95, v95 quad_perm:[1,0,3,2] row_mask:0xf bank_mask:0xf
	v_add_f32_dpp v90, v90, v90 quad_perm:[2,3,0,1] row_mask:0xf bank_mask:0xf
	v_add_f32_dpp v91, v91, v91 quad_perm:[2,3,0,1] row_mask:0xf bank_mask:0xf
	v_add_f32_dpp v92, v92, v92 quad_perm:[2,3,0,1] row_mask:0xf bank_mask:0xf
	v_add_f32_dpp v93, v93, v93 quad_perm:[2,3,0,1] row_mask:0xf bank_mask:0xf
	v_add_f32_dpp v94, v94, v94 quad_perm:[2,3,0,1] row_mask:0xf bank_mask:0xf
	v_add_f32_dpp v95, v95, v95 quad_perm:[2,3,0,1] row_mask:0xf bank_mask:0xf
	v_add_f32_dpp v90, v90, v90 row_half_mirror row_mask:0xf bank_mask:0xf
	v_add_f32_dpp v91, v91, v91 row_half_mirror row_mask:0xf bank_mask:0xf
	v_add_f32_dpp v92, v92, v92 row_half_mirror row_mask:0xf bank_mask:0xf
	v_add_f32_dpp v93, v93, v93 row_half_mirror row_mask:0xf bank_mask:0xf
	v_add_f32_dpp v94, v94, v94 row_half_mirror row_mask:0xf bank_mask:0xf
	v_add_f32_dpp v95, v95, v95 row_half_mirror row_mask:0xf bank_mask:0xf
	v_fmamk_f32 v90, v90, 0x3c800000, v9
	v_fmamk_f32 v91, v91, 0x3c800000, v9
	v_fmamk_f32 v92, v92, 0x3c800000, v9
	v_fmamk_f32 v93, v93, 0x3c800000, v9
	v_fmamk_f32 v94, v94, 0x3c800000, v9
	v_fmamk_f32 v95, v95, 0x3c800000, v9
	v_rsq_f32_e32 v90, v90
	v_rsq_f32_e32 v91, v91
	v_rsq_f32_e32 v92, v92
	v_rsq_f32_e32 v93, v93
	v_rsq_f32_e32 v94, v94
	v_rsq_f32_e32 v95, v95
	v_mul_f32_e32 v168, v168, v58
	v_mul_f32_e32 v169, v169, v59
	v_mul_f32_e32 v170, v170, v60
	v_mul_f32_e32 v171, v171, v61
	v_mul_f32_e32 v172, v172, v62
	v_mul_f32_e32 v173, v173, v63
	v_mul_f32_e32 v174, v174, v64
	v_mul_f32_e32 v175, v175, v65
	v_mul_f32_e32 v182, v182, v74
	v_mul_f32_e32 v183, v183, v75
	v_mul_f32_e32 v184, v184, v76
	v_mul_f32_e32 v185, v185, v77
	v_mul_f32_e32 v186, v186, v78
	v_mul_f32_e32 v187, v187, v79
	v_mul_f32_e32 v188, v188, v80
	v_mul_f32_e32 v189, v189, v81
	v_mul_f32_e32 v196, v196, v58
	v_mul_f32_e32 v197, v197, v59
	v_mul_f32_e32 v198, v198, v60
	v_mul_f32_e32 v199, v199, v61
	v_mul_f32_e32 v200, v200, v62
	v_mul_f32_e32 v201, v201, v63
	v_mul_f32_e32 v202, v202, v64
	v_mul_f32_e32 v203, v203, v65
	v_mul_f32_e32 v210, v210, v74
	v_mul_f32_e32 v211, v211, v75
	v_mul_f32_e32 v212, v212, v76
	v_mul_f32_e32 v213, v213, v77
	v_mul_f32_e32 v214, v214, v78
	v_mul_f32_e32 v215, v215, v79
	v_mul_f32_e32 v216, v216, v80
	v_mul_f32_e32 v217, v217, v81
	v_mul_f32_e32 v224, v224, v58
	v_mul_f32_e32 v225, v225, v59
	v_mul_f32_e32 v226, v226, v60
	v_mul_f32_e32 v227, v227, v61
	v_mul_f32_e32 v228, v228, v62
	v_mul_f32_e32 v229, v229, v63
	v_mul_f32_e32 v230, v230, v64
	v_mul_f32_e32 v231, v231, v65
	v_mul_f32_e32 v238, v238, v74
	v_mul_f32_e32 v239, v239, v75
	v_mul_f32_e32 v240, v240, v76
	v_mul_f32_e32 v241, v241, v77
	v_mul_f32_e32 v242, v242, v78
	v_mul_f32_e32 v243, v243, v79
	v_mul_f32_e32 v244, v244, v80
	v_mul_f32_e32 v245, v245, v81
	v_lshlrev_b32_e32 v176, 16, v164
	v_and_b32_e32 v177, 0xffff0000, v164
	v_lshlrev_b32_e32 v190, 16, v178
	v_and_b32_e32 v191, 0xffff0000, v178
	v_lshlrev_b32_e32 v204, 16, v192
	v_and_b32_e32 v205, 0xffff0000, v192
	v_lshlrev_b32_e32 v218, 16, v206
	v_and_b32_e32 v219, 0xffff0000, v206
	v_lshlrev_b32_e32 v232, 16, v220
	v_and_b32_e32 v233, 0xffff0000, v220
	v_lshlrev_b32_e32 v246, 16, v234
	v_and_b32_e32 v247, 0xffff0000, v234
	v_fmac_f32_e32 v168, v176, v66
	v_fmac_f32_e32 v169, v177, v67
	v_fmac_f32_e32 v182, v190, v82
	v_fmac_f32_e32 v183, v191, v83
	v_fmac_f32_e32 v196, v204, v66
	v_fmac_f32_e32 v197, v205, v67
	v_fmac_f32_e32 v210, v218, v82
	v_fmac_f32_e32 v211, v219, v83
	v_fmac_f32_e32 v224, v232, v66
	v_fmac_f32_e32 v225, v233, v67
	v_fmac_f32_e32 v238, v246, v82
	v_fmac_f32_e32 v239, v247, v83
	v_lshlrev_b32_e32 v176, 16, v165
	v_and_b32_e32 v177, 0xffff0000, v165
	v_lshlrev_b32_e32 v190, 16, v179
	v_and_b32_e32 v191, 0xffff0000, v179
	v_lshlrev_b32_e32 v204, 16, v193
	v_and_b32_e32 v205, 0xffff0000, v193
	v_lshlrev_b32_e32 v218, 16, v207
	v_and_b32_e32 v219, 0xffff0000, v207
	v_lshlrev_b32_e32 v232, 16, v221
	v_and_b32_e32 v233, 0xffff0000, v221
	v_lshlrev_b32_e32 v246, 16, v235
	v_and_b32_e32 v247, 0xffff0000, v235
	v_fmac_f32_e32 v170, v176, v68
	v_fmac_f32_e32 v171, v177, v69
	v_fmac_f32_e32 v184, v190, v84
	v_fmac_f32_e32 v185, v191, v85
	v_fmac_f32_e32 v198, v204, v68
	v_fmac_f32_e32 v199, v205, v69
	v_fmac_f32_e32 v212, v218, v84
	v_fmac_f32_e32 v213, v219, v85
	v_fmac_f32_e32 v226, v232, v68
	v_fmac_f32_e32 v227, v233, v69
	v_fmac_f32_e32 v240, v246, v84
	v_fmac_f32_e32 v241, v247, v85
	v_lshlrev_b32_e32 v176, 16, v166
	v_and_b32_e32 v177, 0xffff0000, v166
	v_lshlrev_b32_e32 v190, 16, v180
	v_and_b32_e32 v191, 0xffff0000, v180
	v_lshlrev_b32_e32 v204, 16, v194
	v_and_b32_e32 v205, 0xffff0000, v194
	v_lshlrev_b32_e32 v218, 16, v208
	v_and_b32_e32 v219, 0xffff0000, v208
	v_lshlrev_b32_e32 v232, 16, v222
	v_and_b32_e32 v233, 0xffff0000, v222
	v_lshlrev_b32_e32 v246, 16, v236
	v_and_b32_e32 v247, 0xffff0000, v236
	v_fmac_f32_e32 v172, v176, v70
	v_fmac_f32_e32 v173, v177, v71
	v_fmac_f32_e32 v186, v190, v86
	v_fmac_f32_e32 v187, v191, v87
	v_fmac_f32_e32 v200, v204, v70
	v_fmac_f32_e32 v201, v205, v71
	v_fmac_f32_e32 v214, v218, v86
	v_fmac_f32_e32 v215, v219, v87
	v_fmac_f32_e32 v228, v232, v70
	v_fmac_f32_e32 v229, v233, v71
	v_fmac_f32_e32 v242, v246, v86
	v_fmac_f32_e32 v243, v247, v87
	v_lshlrev_b32_e32 v176, 16, v167
	v_and_b32_e32 v177, 0xffff0000, v167
	v_lshlrev_b32_e32 v190, 16, v181
	v_and_b32_e32 v191, 0xffff0000, v181
	v_lshlrev_b32_e32 v204, 16, v195
	v_and_b32_e32 v205, 0xffff0000, v195
	v_lshlrev_b32_e32 v218, 16, v209
	v_and_b32_e32 v219, 0xffff0000, v209
	v_lshlrev_b32_e32 v232, 16, v223
	v_and_b32_e32 v233, 0xffff0000, v223
	v_lshlrev_b32_e32 v246, 16, v237
	v_and_b32_e32 v247, 0xffff0000, v237
	v_fmac_f32_e32 v174, v176, v72
	v_fmac_f32_e32 v175, v177, v73
	v_fmac_f32_e32 v188, v190, v88
	v_fmac_f32_e32 v189, v191, v89
	v_fmac_f32_e32 v202, v204, v72
	v_fmac_f32_e32 v203, v205, v73
	v_fmac_f32_e32 v216, v218, v88
	v_fmac_f32_e32 v217, v219, v89
	v_fmac_f32_e32 v230, v232, v72
	v_fmac_f32_e32 v231, v233, v73
	v_fmac_f32_e32 v244, v246, v88
	v_fmac_f32_e32 v245, v247, v89
	v_mul_f32_e32 v168, v168, v90
	v_mul_f32_e32 v169, v169, v90
	v_mul_f32_e32 v170, v170, v90
	v_mul_f32_e32 v171, v171, v90
	v_mul_f32_e32 v172, v172, v90
	v_mul_f32_e32 v173, v173, v90
	v_mul_f32_e32 v174, v174, v90
	v_mul_f32_e32 v175, v175, v90
	v_mul_f32_e32 v182, v182, v91
	v_mul_f32_e32 v183, v183, v91
	v_mul_f32_e32 v184, v184, v91
	v_mul_f32_e32 v185, v185, v91
	v_mul_f32_e32 v186, v186, v91
	v_mul_f32_e32 v187, v187, v91
	v_mul_f32_e32 v188, v188, v91
	v_mul_f32_e32 v189, v189, v91
	v_mul_f32_e32 v196, v196, v92
	v_mul_f32_e32 v197, v197, v92
	v_mul_f32_e32 v198, v198, v92
	v_mul_f32_e32 v199, v199, v92
	v_mul_f32_e32 v200, v200, v92
	v_mul_f32_e32 v201, v201, v92
	v_mul_f32_e32 v202, v202, v92
	v_mul_f32_e32 v203, v203, v92
	v_mul_f32_e32 v210, v210, v93
	v_mul_f32_e32 v211, v211, v93
	v_mul_f32_e32 v212, v212, v93
	v_mul_f32_e32 v213, v213, v93
	v_mul_f32_e32 v214, v214, v93
	v_mul_f32_e32 v215, v215, v93
	v_mul_f32_e32 v216, v216, v93
	v_mul_f32_e32 v217, v217, v93
	v_mul_f32_e32 v224, v224, v94
	v_mul_f32_e32 v225, v225, v94
	v_mul_f32_e32 v226, v226, v94
	v_mul_f32_e32 v227, v227, v94
	v_mul_f32_e32 v228, v228, v94
	v_mul_f32_e32 v229, v229, v94
	v_mul_f32_e32 v230, v230, v94
	v_mul_f32_e32 v231, v231, v94
	v_mul_f32_e32 v238, v238, v95
	v_mul_f32_e32 v239, v239, v95
	v_mul_f32_e32 v240, v240, v95
	v_mul_f32_e32 v241, v241, v95
	v_mul_f32_e32 v242, v242, v95
	v_mul_f32_e32 v243, v243, v95
	v_mul_f32_e32 v244, v244, v95
	v_mul_f32_e32 v245, v245, v95
	v_cvt_pk_bf16_f32 v164, v168, v169
	v_cvt_pk_bf16_f32 v165, v170, v171
	v_cvt_pk_bf16_f32 v166, v172, v173
	v_cvt_pk_bf16_f32 v167, v174, v175
	v_cvt_pk_bf16_f32 v178, v182, v183
	v_cvt_pk_bf16_f32 v179, v184, v185
	v_cvt_pk_bf16_f32 v180, v186, v187
	v_cvt_pk_bf16_f32 v181, v188, v189
	v_cvt_pk_bf16_f32 v192, v196, v197
	v_cvt_pk_bf16_f32 v193, v198, v199
	v_cvt_pk_bf16_f32 v194, v200, v201
	v_cvt_pk_bf16_f32 v195, v202, v203
	v_cvt_pk_bf16_f32 v206, v210, v211
	v_cvt_pk_bf16_f32 v207, v212, v213
	v_cvt_pk_bf16_f32 v208, v214, v215
	v_cvt_pk_bf16_f32 v209, v216, v217
	v_cvt_pk_bf16_f32 v220, v224, v225
	v_cvt_pk_bf16_f32 v221, v226, v227
	v_cvt_pk_bf16_f32 v222, v228, v229
	v_cvt_pk_bf16_f32 v223, v230, v231
	v_cvt_pk_bf16_f32 v234, v238, v239
	v_cvt_pk_bf16_f32 v235, v240, v241
	v_cvt_pk_bf16_f32 v236, v242, v243
	v_cvt_pk_bf16_f32 v237, v244, v245
	s_add_u32 s22, s8, 0x480000
	s_addc_u32 s23, s9, 0
	global_store_dwordx4 v1, v[164:167], s[6:7]
	s_mov_b64 exec, s[44:45]
	global_store_dwordx4 v4, v[178:181], s[8:9]
	s_mov_b64 exec, s[48:49]
	global_store_dwordx4 v4, v[120:123], s[22:23]
	s_mov_b64 exec, s[60:61]
	s_add_u32 s6, s6, 0x400000
	s_addc_u32 s7, s7, 0
	s_add_u32 s8, s8, 0x90000
	s_addc_u32 s9, s9, 0
	s_add_u32 s22, s8, 0x480000
	s_addc_u32 s23, s9, 0
	global_store_dwordx4 v1, v[192:195], s[6:7]
	s_mov_b64 exec, s[44:45]
	global_store_dwordx4 v4, v[206:209], s[8:9]
	s_mov_b64 exec, s[48:49]
	global_store_dwordx4 v4, v[128:131], s[22:23]
	s_mov_b64 exec, s[60:61]
	s_add_u32 s6, s6, 0x400000
	s_addc_u32 s7, s7, 0
	s_add_u32 s8, s8, 0x90000
	s_addc_u32 s9, s9, 0
	s_add_u32 s22, s8, 0x480000
	s_addc_u32 s23, s9, 0
	global_store_dwordx4 v1, v[220:223], s[6:7]
	s_mov_b64 exec, s[44:45]
	global_store_dwordx4 v4, v[234:237], s[8:9]
	s_mov_b64 exec, s[48:49]
	global_store_dwordx4 v4, v[136:139], s[22:23]
	s_mov_b64 exec, s[60:61]
	s_add_u32 s6, s6, 0x400000
	s_addc_u32 s7, s7, 0
	s_add_u32 s8, s8, 0x90000
	s_addc_u32 s9, s9, 0
	global_load_dwordx4 v[116:119], v1, s[4:5]
	global_load_dwordx4 v[120:123], v2, s[4:5]
	s_add_u32 s4, s4, 0x600000
	s_addc_u32 s5, s5, 0
	global_load_dwordx4 v[124:127], v1, s[4:5]
	global_load_dwordx4 v[128:131], v2, s[4:5]
	s_add_u32 s4, s4, 0x600000
	s_addc_u32 s5, s5, 0
	global_load_dwordx4 v[132:135], v1, s[4:5]
	global_load_dwordx4 v[136:139], v2, s[4:5]
	s_add_u32 s4, s4, 0x600000
	s_addc_u32 s5, s5, 0
	s_waitcnt vmcnt(15)
	v_lshlrev_b32_e32 v168, 16, v140
	v_and_b32_e32 v169, 0xffff0000, v140
	v_lshlrev_b32_e32 v170, 16, v141
	v_and_b32_e32 v171, 0xffff0000, v141
	v_lshlrev_b32_e32 v172, 16, v142
	v_and_b32_e32 v173, 0xffff0000, v142
	v_lshlrev_b32_e32 v174, 16, v143
	v_and_b32_e32 v175, 0xffff0000, v143
	v_lshlrev_b32_e32 v182, 16, v144
	v_and_b32_e32 v183, 0xffff0000, v144
	v_lshlrev_b32_e32 v184, 16, v145
	v_and_b32_e32 v185, 0xffff0000, v145
	v_lshlrev_b32_e32 v186, 16, v146
	v_and_b32_e32 v187, 0xffff0000, v146
	v_lshlrev_b32_e32 v188, 16, v147
	v_and_b32_e32 v189, 0xffff0000, v147
	v_lshlrev_b32_e32 v196, 16, v148
	v_and_b32_e32 v197, 0xffff0000, v148
	v_lshlrev_b32_e32 v198, 16, v149
	v_and_b32_e32 v199, 0xffff0000, v149
	v_lshlrev_b32_e32 v200, 16, v150
	v_and_b32_e32 v201, 0xffff0000, v150
	v_lshlrev_b32_e32 v202, 16, v151
	v_and_b32_e32 v203, 0xffff0000, v151
	v_lshlrev_b32_e32 v210, 16, v152
	v_and_b32_e32 v211, 0xffff0000, v152
	v_lshlrev_b32_e32 v212, 16, v153
	v_and_b32_e32 v213, 0xffff0000, v153
	v_lshlrev_b32_e32 v214, 16, v154
	v_and_b32_e32 v215, 0xffff0000, v154
	v_lshlrev_b32_e32 v216, 16, v155
	v_and_b32_e32 v217, 0xffff0000, v155
	v_lshlrev_b32_e32 v224, 16, v156
	v_and_b32_e32 v225, 0xffff0000, v156
	v_lshlrev_b32_e32 v226, 16, v157
	v_and_b32_e32 v227, 0xffff0000, v157
	v_lshlrev_b32_e32 v228, 16, v158
	v_and_b32_e32 v229, 0xffff0000, v158
	v_lshlrev_b32_e32 v230, 16, v159
	v_and_b32_e32 v231, 0xffff0000, v159
	v_lshlrev_b32_e32 v238, 16, v160
	v_and_b32_e32 v239, 0xffff0000, v160
	v_lshlrev_b32_e32 v240, 16, v161
	v_and_b32_e32 v241, 0xffff0000, v161
	v_lshlrev_b32_e32 v242, 16, v162
	v_and_b32_e32 v243, 0xffff0000, v162
	v_lshlrev_b32_e32 v244, 16, v163
	v_and_b32_e32 v245, 0xffff0000, v163
	v_mov_b32_dpp v164, v140 row_half_mirror row_mask:0xf bank_mask:0xf
	v_mov_b32_dpp v165, v141 row_half_mirror row_mask:0xf bank_mask:0xf
	v_mov_b32_dpp v166, v142 row_half_mirror row_mask:0xf bank_mask:0xf
	v_mov_b32_dpp v167, v143 row_half_mirror row_mask:0xf bank_mask:0xf
	v_mov_b32_dpp v178, v144 row_half_mirror row_mask:0xf bank_mask:0xf
	v_mov_b32_dpp v179, v145 row_half_mirror row_mask:0xf bank_mask:0xf
	v_mov_b32_dpp v180, v146 row_half_mirror row_mask:0xf bank_mask:0xf
	v_mov_b32_dpp v181, v147 row_half_mirror row_mask:0xf bank_mask:0xf
	v_mov_b32_dpp v192, v148 row_half_mirror row_mask:0xf bank_mask:0xf
	v_mov_b32_dpp v193, v149 row_half_mirror row_mask:0xf bank_mask:0xf
	v_mov_b32_dpp v194, v150 row_half_mirror row_mask:0xf bank_mask:0xf
	v_mov_b32_dpp v195, v151 row_half_mirror row_mask:0xf bank_mask:0xf
	v_mov_b32_dpp v206, v152 row_half_mirror row_mask:0xf bank_mask:0xf
	v_mov_b32_dpp v207, v153 row_half_mirror row_mask:0xf bank_mask:0xf
	v_mov_b32_dpp v208, v154 row_half_mirror row_mask:0xf bank_mask:0xf
	v_mov_b32_dpp v209, v155 row_half_mirror row_mask:0xf bank_mask:0xf
	v_mov_b32_dpp v220, v156 row_half_mirror row_mask:0xf bank_mask:0xf
	v_mov_b32_dpp v221, v157 row_half_mirror row_mask:0xf bank_mask:0xf
	v_mov_b32_dpp v222, v158 row_half_mirror row_mask:0xf bank_mask:0xf
	v_mov_b32_dpp v223, v159 row_half_mirror row_mask:0xf bank_mask:0xf
	v_mov_b32_dpp v234, v160 row_half_mirror row_mask:0xf bank_mask:0xf
	v_mov_b32_dpp v235, v161 row_half_mirror row_mask:0xf bank_mask:0xf
	v_mov_b32_dpp v236, v162 row_half_mirror row_mask:0xf bank_mask:0xf
	v_mov_b32_dpp v237, v163 row_half_mirror row_mask:0xf bank_mask:0xf
	v_mul_f32_e32 v90, v168, v168
	v_mul_f32_e32 v91, v182, v182
	v_mul_f32_e32 v92, v196, v196
	v_mul_f32_e32 v93, v210, v210
	v_mul_f32_e32 v94, v224, v224
	v_mul_f32_e32 v95, v238, v238
	v_fmac_f32_e32 v90, v169, v169
	v_fmac_f32_e32 v91, v183, v183
	v_fmac_f32_e32 v92, v197, v197
	v_fmac_f32_e32 v93, v211, v211
	v_fmac_f32_e32 v94, v225, v225
	v_fmac_f32_e32 v95, v239, v239
	v_fmac_f32_e32 v90, v170, v170
	v_fmac_f32_e32 v91, v184, v184
	v_fmac_f32_e32 v92, v198, v198
	v_fmac_f32_e32 v93, v212, v212
	v_fmac_f32_e32 v94, v226, v226
	v_fmac_f32_e32 v95, v240, v240
	v_fmac_f32_e32 v90, v171, v171
	v_fmac_f32_e32 v91, v185, v185
	v_fmac_f32_e32 v92, v199, v199
	v_fmac_f32_e32 v93, v213, v213
	v_fmac_f32_e32 v94, v227, v227
	v_fmac_f32_e32 v95, v241, v241
	v_fmac_f32_e32 v90, v172, v172
	v_fmac_f32_e32 v91, v186, v186
	v_fmac_f32_e32 v92, v200, v200
	v_fmac_f32_e32 v93, v214, v214
	v_fmac_f32_e32 v94, v228, v228
	v_fmac_f32_e32 v95, v242, v242
	v_fmac_f32_e32 v90, v173, v173
	v_fmac_f32_e32 v91, v187, v187
	v_fmac_f32_e32 v92, v201, v201
	v_fmac_f32_e32 v93, v215, v215
	v_fmac_f32_e32 v94, v229, v229
	v_fmac_f32_e32 v95, v243, v243
	v_fmac_f32_e32 v90, v174, v174
	v_fmac_f32_e32 v91, v188, v188
	v_fmac_f32_e32 v92, v202, v202
	v_fmac_f32_e32 v93, v216, v216
	v_fmac_f32_e32 v94, v230, v230
	v_fmac_f32_e32 v95, v244, v244
	v_fmac_f32_e32 v90, v175, v175
	v_fmac_f32_e32 v91, v189, v189
	v_fmac_f32_e32 v92, v203, v203
	v_fmac_f32_e32 v93, v217, v217
	v_fmac_f32_e32 v94, v231, v231
	v_fmac_f32_e32 v95, v245, v245
	v_mov_b32_dpp v164, v164 quad_perm:[3,2,1,0] row_mask:0xf bank_mask:0xf
	v_mov_b32_dpp v165, v165 quad_perm:[3,2,1,0] row_mask:0xf bank_mask:0xf
	v_mov_b32_dpp v166, v166 quad_perm:[3,2,1,0] row_mask:0xf bank_mask:0xf
	v_mov_b32_dpp v167, v167 quad_perm:[3,2,1,0] row_mask:0xf bank_mask:0xf
	v_mov_b32_dpp v178, v178 quad_perm:[3,2,1,0] row_mask:0xf bank_mask:0xf
	v_mov_b32_dpp v179, v179 quad_perm:[3,2,1,0] row_mask:0xf bank_mask:0xf
	v_mov_b32_dpp v180, v180 quad_perm:[3,2,1,0] row_mask:0xf bank_mask:0xf
	v_mov_b32_dpp v181, v181 quad_perm:[3,2,1,0] row_mask:0xf bank_mask:0xf
	v_mov_b32_dpp v192, v192 quad_perm:[3,2,1,0] row_mask:0xf bank_mask:0xf
	v_mov_b32_dpp v193, v193 quad_perm:[3,2,1,0] row_mask:0xf bank_mask:0xf
	v_mov_b32_dpp v194, v194 quad_perm:[3,2,1,0] row_mask:0xf bank_mask:0xf
	v_mov_b32_dpp v195, v195 quad_perm:[3,2,1,0] row_mask:0xf bank_mask:0xf
	v_mov_b32_dpp v206, v206 quad_perm:[3,2,1,0] row_mask:0xf bank_mask:0xf
	v_mov_b32_dpp v207, v207 quad_perm:[3,2,1,0] row_mask:0xf bank_mask:0xf
	v_mov_b32_dpp v208, v208 quad_perm:[3,2,1,0] row_mask:0xf bank_mask:0xf
	v_mov_b32_dpp v209, v209 quad_perm:[3,2,1,0] row_mask:0xf bank_mask:0xf
	v_mov_b32_dpp v220, v220 quad_perm:[3,2,1,0] row_mask:0xf bank_mask:0xf
	v_mov_b32_dpp v221, v221 quad_perm:[3,2,1,0] row_mask:0xf bank_mask:0xf
	v_mov_b32_dpp v222, v222 quad_perm:[3,2,1,0] row_mask:0xf bank_mask:0xf
	v_mov_b32_dpp v223, v223 quad_perm:[3,2,1,0] row_mask:0xf bank_mask:0xf
	v_mov_b32_dpp v234, v234 quad_perm:[3,2,1,0] row_mask:0xf bank_mask:0xf
	v_mov_b32_dpp v235, v235 quad_perm:[3,2,1,0] row_mask:0xf bank_mask:0xf
	v_mov_b32_dpp v236, v236 quad_perm:[3,2,1,0] row_mask:0xf bank_mask:0xf
	v_mov_b32_dpp v237, v237 quad_perm:[3,2,1,0] row_mask:0xf bank_mask:0xf
	v_add_f32_dpp v90, v90, v90 quad_perm:[1,0,3,2] row_mask:0xf bank_mask:0xf
	v_add_f32_dpp v91, v91, v91 quad_perm:[1,0,3,2] row_mask:0xf bank_mask:0xf
	v_add_f32_dpp v92, v92, v92 quad_perm:[1,0,3,2] row_mask:0xf bank_mask:0xf
	v_add_f32_dpp v93, v93, v93 quad_perm:[1,0,3,2] row_mask:0xf bank_mask:0xf
	v_add_f32_dpp v94, v94, v94 quad_perm:[1,0,3,2] row_mask:0xf bank_mask:0xf
	v_add_f32_dpp v95, v95, v95 quad_perm:[1,0,3,2] row_mask:0xf bank_mask:0xf
	v_add_f32_dpp v90, v90, v90 quad_perm:[2,3,0,1] row_mask:0xf bank_mask:0xf
	v_add_f32_dpp v91, v91, v91 quad_perm:[2,3,0,1] row_mask:0xf bank_mask:0xf
	v_add_f32_dpp v92, v92, v92 quad_perm:[2,3,0,1] row_mask:0xf bank_mask:0xf
	v_add_f32_dpp v93, v93, v93 quad_perm:[2,3,0,1] row_mask:0xf bank_mask:0xf
	v_add_f32_dpp v94, v94, v94 quad_perm:[2,3,0,1] row_mask:0xf bank_mask:0xf
	v_add_f32_dpp v95, v95, v95 quad_perm:[2,3,0,1] row_mask:0xf bank_mask:0xf
	v_add_f32_dpp v90, v90, v90 row_half_mirror row_mask:0xf bank_mask:0xf
	v_add_f32_dpp v91, v91, v91 row_half_mirror row_mask:0xf bank_mask:0xf
	v_add_f32_dpp v92, v92, v92 row_half_mirror row_mask:0xf bank_mask:0xf
	v_add_f32_dpp v93, v93, v93 row_half_mirror row_mask:0xf bank_mask:0xf
	v_add_f32_dpp v94, v94, v94 row_half_mirror row_mask:0xf bank_mask:0xf
	v_add_f32_dpp v95, v95, v95 row_half_mirror row_mask:0xf bank_mask:0xf
	v_fmamk_f32 v90, v90, 0x3c800000, v9
	v_fmamk_f32 v91, v91, 0x3c800000, v9
	v_fmamk_f32 v92, v92, 0x3c800000, v9
	v_fmamk_f32 v93, v93, 0x3c800000, v9
	v_fmamk_f32 v94, v94, 0x3c800000, v9
	v_fmamk_f32 v95, v95, 0x3c800000, v9
	v_rsq_f32_e32 v90, v90
	v_rsq_f32_e32 v91, v91
	v_rsq_f32_e32 v92, v92
	v_rsq_f32_e32 v93, v93
	v_rsq_f32_e32 v94, v94
	v_rsq_f32_e32 v95, v95
	v_mul_f32_e32 v168, v168, v58
	v_mul_f32_e32 v169, v169, v59
	v_mul_f32_e32 v170, v170, v60
	v_mul_f32_e32 v171, v171, v61
	v_mul_f32_e32 v172, v172, v62
	v_mul_f32_e32 v173, v173, v63
	v_mul_f32_e32 v174, v174, v64
	v_mul_f32_e32 v175, v175, v65
	v_mul_f32_e32 v182, v182, v74
	v_mul_f32_e32 v183, v183, v75
	v_mul_f32_e32 v184, v184, v76
	v_mul_f32_e32 v185, v185, v77
	v_mul_f32_e32 v186, v186, v78
	v_mul_f32_e32 v187, v187, v79
	v_mul_f32_e32 v188, v188, v80
	v_mul_f32_e32 v189, v189, v81
	v_mul_f32_e32 v196, v196, v58
	v_mul_f32_e32 v197, v197, v59
	v_mul_f32_e32 v198, v198, v60
	v_mul_f32_e32 v199, v199, v61
	v_mul_f32_e32 v200, v200, v62
	v_mul_f32_e32 v201, v201, v63
	v_mul_f32_e32 v202, v202, v64
	v_mul_f32_e32 v203, v203, v65
	v_mul_f32_e32 v210, v210, v74
	v_mul_f32_e32 v211, v211, v75
	v_mul_f32_e32 v212, v212, v76
	v_mul_f32_e32 v213, v213, v77
	v_mul_f32_e32 v214, v214, v78
	v_mul_f32_e32 v215, v215, v79
	v_mul_f32_e32 v216, v216, v80
	v_mul_f32_e32 v217, v217, v81
	v_mul_f32_e32 v224, v224, v58
	v_mul_f32_e32 v225, v225, v59
	v_mul_f32_e32 v226, v226, v60
	v_mul_f32_e32 v227, v227, v61
	v_mul_f32_e32 v228, v228, v62
	v_mul_f32_e32 v229, v229, v63
	v_mul_f32_e32 v230, v230, v64
	v_mul_f32_e32 v231, v231, v65
	v_mul_f32_e32 v238, v238, v74
	v_mul_f32_e32 v239, v239, v75
	v_mul_f32_e32 v240, v240, v76
	v_mul_f32_e32 v241, v241, v77
	v_mul_f32_e32 v242, v242, v78
	v_mul_f32_e32 v243, v243, v79
	v_mul_f32_e32 v244, v244, v80
	v_mul_f32_e32 v245, v245, v81
	v_lshlrev_b32_e32 v176, 16, v164
	v_and_b32_e32 v177, 0xffff0000, v164
	v_lshlrev_b32_e32 v190, 16, v178
	v_and_b32_e32 v191, 0xffff0000, v178
	v_lshlrev_b32_e32 v204, 16, v192
	v_and_b32_e32 v205, 0xffff0000, v192
	v_lshlrev_b32_e32 v218, 16, v206
	v_and_b32_e32 v219, 0xffff0000, v206
	v_lshlrev_b32_e32 v232, 16, v220
	v_and_b32_e32 v233, 0xffff0000, v220
	v_lshlrev_b32_e32 v246, 16, v234
	v_and_b32_e32 v247, 0xffff0000, v234
	v_fmac_f32_e32 v168, v176, v66
	v_fmac_f32_e32 v169, v177, v67
	v_fmac_f32_e32 v182, v190, v82
	v_fmac_f32_e32 v183, v191, v83
	v_fmac_f32_e32 v196, v204, v66
	v_fmac_f32_e32 v197, v205, v67
	v_fmac_f32_e32 v210, v218, v82
	v_fmac_f32_e32 v211, v219, v83
	v_fmac_f32_e32 v224, v232, v66
	v_fmac_f32_e32 v225, v233, v67
	v_fmac_f32_e32 v238, v246, v82
	v_fmac_f32_e32 v239, v247, v83
	v_lshlrev_b32_e32 v176, 16, v165
	v_and_b32_e32 v177, 0xffff0000, v165
	v_lshlrev_b32_e32 v190, 16, v179
	v_and_b32_e32 v191, 0xffff0000, v179
	v_lshlrev_b32_e32 v204, 16, v193
	v_and_b32_e32 v205, 0xffff0000, v193
	v_lshlrev_b32_e32 v218, 16, v207
	v_and_b32_e32 v219, 0xffff0000, v207
	v_lshlrev_b32_e32 v232, 16, v221
	v_and_b32_e32 v233, 0xffff0000, v221
	v_lshlrev_b32_e32 v246, 16, v235
	v_and_b32_e32 v247, 0xffff0000, v235
	v_fmac_f32_e32 v170, v176, v68
	v_fmac_f32_e32 v171, v177, v69
	v_fmac_f32_e32 v184, v190, v84
	v_fmac_f32_e32 v185, v191, v85
	v_fmac_f32_e32 v198, v204, v68
	v_fmac_f32_e32 v199, v205, v69
	v_fmac_f32_e32 v212, v218, v84
	v_fmac_f32_e32 v213, v219, v85
	v_fmac_f32_e32 v226, v232, v68
	v_fmac_f32_e32 v227, v233, v69
	v_fmac_f32_e32 v240, v246, v84
	v_fmac_f32_e32 v241, v247, v85
	v_lshlrev_b32_e32 v176, 16, v166
	v_and_b32_e32 v177, 0xffff0000, v166
	v_lshlrev_b32_e32 v190, 16, v180
	v_and_b32_e32 v191, 0xffff0000, v180
	v_lshlrev_b32_e32 v204, 16, v194
	v_and_b32_e32 v205, 0xffff0000, v194
	v_lshlrev_b32_e32 v218, 16, v208
	v_and_b32_e32 v219, 0xffff0000, v208
	v_lshlrev_b32_e32 v232, 16, v222
	v_and_b32_e32 v233, 0xffff0000, v222
	v_lshlrev_b32_e32 v246, 16, v236
	v_and_b32_e32 v247, 0xffff0000, v236
	v_fmac_f32_e32 v172, v176, v70
	v_fmac_f32_e32 v173, v177, v71
	v_fmac_f32_e32 v186, v190, v86
	v_fmac_f32_e32 v187, v191, v87
	v_fmac_f32_e32 v200, v204, v70
	v_fmac_f32_e32 v201, v205, v71
	v_fmac_f32_e32 v214, v218, v86
	v_fmac_f32_e32 v215, v219, v87
	v_fmac_f32_e32 v228, v232, v70
	v_fmac_f32_e32 v229, v233, v71
	v_fmac_f32_e32 v242, v246, v86
	v_fmac_f32_e32 v243, v247, v87
	v_lshlrev_b32_e32 v176, 16, v167
	v_and_b32_e32 v177, 0xffff0000, v167
	v_lshlrev_b32_e32 v190, 16, v181
	v_and_b32_e32 v191, 0xffff0000, v181
	v_lshlrev_b32_e32 v204, 16, v195
	v_and_b32_e32 v205, 0xffff0000, v195
	v_lshlrev_b32_e32 v218, 16, v209
	v_and_b32_e32 v219, 0xffff0000, v209
	v_lshlrev_b32_e32 v232, 16, v223
	v_and_b32_e32 v233, 0xffff0000, v223
	v_lshlrev_b32_e32 v246, 16, v237
	v_and_b32_e32 v247, 0xffff0000, v237
	v_fmac_f32_e32 v174, v176, v72
	v_fmac_f32_e32 v175, v177, v73
	v_fmac_f32_e32 v188, v190, v88
	v_fmac_f32_e32 v189, v191, v89
	v_fmac_f32_e32 v202, v204, v72
	v_fmac_f32_e32 v203, v205, v73
	v_fmac_f32_e32 v216, v218, v88
	v_fmac_f32_e32 v217, v219, v89
	v_fmac_f32_e32 v230, v232, v72
	v_fmac_f32_e32 v231, v233, v73
	v_fmac_f32_e32 v244, v246, v88
	v_fmac_f32_e32 v245, v247, v89
	v_mul_f32_e32 v168, v168, v90
	v_mul_f32_e32 v169, v169, v90
	v_mul_f32_e32 v170, v170, v90
	v_mul_f32_e32 v171, v171, v90
	v_mul_f32_e32 v172, v172, v90
	v_mul_f32_e32 v173, v173, v90
	v_mul_f32_e32 v174, v174, v90
	v_mul_f32_e32 v175, v175, v90
	v_mul_f32_e32 v182, v182, v91
	v_mul_f32_e32 v183, v183, v91
	v_mul_f32_e32 v184, v184, v91
	v_mul_f32_e32 v185, v185, v91
	v_mul_f32_e32 v186, v186, v91
	v_mul_f32_e32 v187, v187, v91
	v_mul_f32_e32 v188, v188, v91
	v_mul_f32_e32 v189, v189, v91
	v_mul_f32_e32 v196, v196, v92
	v_mul_f32_e32 v197, v197, v92
	v_mul_f32_e32 v198, v198, v92
	v_mul_f32_e32 v199, v199, v92
	v_mul_f32_e32 v200, v200, v92
	v_mul_f32_e32 v201, v201, v92
	v_mul_f32_e32 v202, v202, v92
	v_mul_f32_e32 v203, v203, v92
	v_mul_f32_e32 v210, v210, v93
	v_mul_f32_e32 v211, v211, v93
	v_mul_f32_e32 v212, v212, v93
	v_mul_f32_e32 v213, v213, v93
	v_mul_f32_e32 v214, v214, v93
	v_mul_f32_e32 v215, v215, v93
	v_mul_f32_e32 v216, v216, v93
	v_mul_f32_e32 v217, v217, v93
	v_mul_f32_e32 v224, v224, v94
	v_mul_f32_e32 v225, v225, v94
	v_mul_f32_e32 v226, v226, v94
	v_mul_f32_e32 v227, v227, v94
	v_mul_f32_e32 v228, v228, v94
	v_mul_f32_e32 v229, v229, v94
	v_mul_f32_e32 v230, v230, v94
	v_mul_f32_e32 v231, v231, v94
	v_mul_f32_e32 v238, v238, v95
	v_mul_f32_e32 v239, v239, v95
	v_mul_f32_e32 v240, v240, v95
	v_mul_f32_e32 v241, v241, v95
	v_mul_f32_e32 v242, v242, v95
	v_mul_f32_e32 v243, v243, v95
	v_mul_f32_e32 v244, v244, v95
	v_mul_f32_e32 v245, v245, v95
	v_cvt_pk_bf16_f32 v164, v168, v169
	v_cvt_pk_bf16_f32 v165, v170, v171
	v_cvt_pk_bf16_f32 v166, v172, v173
	v_cvt_pk_bf16_f32 v167, v174, v175
	v_cvt_pk_bf16_f32 v178, v182, v183
	v_cvt_pk_bf16_f32 v179, v184, v185
	v_cvt_pk_bf16_f32 v180, v186, v187
	v_cvt_pk_bf16_f32 v181, v188, v189
	v_cvt_pk_bf16_f32 v192, v196, v197
	v_cvt_pk_bf16_f32 v193, v198, v199
	v_cvt_pk_bf16_f32 v194, v200, v201
	v_cvt_pk_bf16_f32 v195, v202, v203
	v_cvt_pk_bf16_f32 v206, v210, v211
	v_cvt_pk_bf16_f32 v207, v212, v213
	v_cvt_pk_bf16_f32 v208, v214, v215
	v_cvt_pk_bf16_f32 v209, v216, v217
	v_cvt_pk_bf16_f32 v220, v224, v225
	v_cvt_pk_bf16_f32 v221, v226, v227
	v_cvt_pk_bf16_f32 v222, v228, v229
	v_cvt_pk_bf16_f32 v223, v230, v231
	v_cvt_pk_bf16_f32 v234, v238, v239
	v_cvt_pk_bf16_f32 v235, v240, v241
	v_cvt_pk_bf16_f32 v236, v242, v243
	v_cvt_pk_bf16_f32 v237, v244, v245
	s_add_u32 s22, s8, 0x480000
	s_addc_u32 s23, s9, 0
	global_store_dwordx4 v1, v[164:167], s[6:7]
	s_mov_b64 exec, s[44:45]
	global_store_dwordx4 v4, v[178:181], s[8:9]
	s_mov_b64 exec, s[48:49]
	global_store_dwordx4 v4, v[144:147], s[22:23]
	s_mov_b64 exec, s[60:61]
	s_add_u32 s6, s6, 0x400000
	s_addc_u32 s7, s7, 0
	s_add_u32 s8, s8, 0x90000
	s_addc_u32 s9, s9, 0
	s_add_u32 s22, s8, 0x480000
	s_addc_u32 s23, s9, 0
	global_store_dwordx4 v1, v[192:195], s[6:7]
	s_mov_b64 exec, s[44:45]
	global_store_dwordx4 v4, v[206:209], s[8:9]
	s_mov_b64 exec, s[48:49]
	global_store_dwordx4 v4, v[152:155], s[22:23]
	s_mov_b64 exec, s[60:61]
	s_add_u32 s6, s6, 0x400000
	s_addc_u32 s7, s7, 0
	s_add_u32 s8, s8, 0x90000
	s_addc_u32 s9, s9, 0
	s_add_u32 s22, s8, 0x480000
	s_addc_u32 s23, s9, 0
	global_store_dwordx4 v1, v[220:223], s[6:7]
	s_mov_b64 exec, s[44:45]
	global_store_dwordx4 v4, v[234:237], s[8:9]
	s_mov_b64 exec, s[48:49]
	global_store_dwordx4 v4, v[160:163], s[22:23]
	s_mov_b64 exec, s[60:61]
	s_add_u32 s6, s6, 0x400000
	s_addc_u32 s7, s7, 0
	s_add_u32 s8, s8, 0x90000
	s_addc_u32 s9, s9, 0
	s_waitcnt vmcnt(9)
	v_lshlrev_b32_e32 v168, 16, v116
	v_and_b32_e32 v169, 0xffff0000, v116
	v_lshlrev_b32_e32 v170, 16, v117
	v_and_b32_e32 v171, 0xffff0000, v117
	v_lshlrev_b32_e32 v172, 16, v118
	v_and_b32_e32 v173, 0xffff0000, v118
	v_lshlrev_b32_e32 v174, 16, v119
	v_and_b32_e32 v175, 0xffff0000, v119
	v_lshlrev_b32_e32 v182, 16, v120
	v_and_b32_e32 v183, 0xffff0000, v120
	v_lshlrev_b32_e32 v184, 16, v121
	v_and_b32_e32 v185, 0xffff0000, v121
	v_lshlrev_b32_e32 v186, 16, v122
	v_and_b32_e32 v187, 0xffff0000, v122
	v_lshlrev_b32_e32 v188, 16, v123
	v_and_b32_e32 v189, 0xffff0000, v123
	v_lshlrev_b32_e32 v196, 16, v124
	v_and_b32_e32 v197, 0xffff0000, v124
	v_lshlrev_b32_e32 v198, 16, v125
	v_and_b32_e32 v199, 0xffff0000, v125
	v_lshlrev_b32_e32 v200, 16, v126
	v_and_b32_e32 v201, 0xffff0000, v126
	v_lshlrev_b32_e32 v202, 16, v127
	v_and_b32_e32 v203, 0xffff0000, v127
	v_lshlrev_b32_e32 v210, 16, v128
	v_and_b32_e32 v211, 0xffff0000, v128
	v_lshlrev_b32_e32 v212, 16, v129
	v_and_b32_e32 v213, 0xffff0000, v129
	v_lshlrev_b32_e32 v214, 16, v130
	v_and_b32_e32 v215, 0xffff0000, v130
	v_lshlrev_b32_e32 v216, 16, v131
	v_and_b32_e32 v217, 0xffff0000, v131
	v_lshlrev_b32_e32 v224, 16, v132
	v_and_b32_e32 v225, 0xffff0000, v132
	v_lshlrev_b32_e32 v226, 16, v133
	v_and_b32_e32 v227, 0xffff0000, v133
	v_lshlrev_b32_e32 v228, 16, v134
	v_and_b32_e32 v229, 0xffff0000, v134
	v_lshlrev_b32_e32 v230, 16, v135
	v_and_b32_e32 v231, 0xffff0000, v135
	v_lshlrev_b32_e32 v238, 16, v136
	v_and_b32_e32 v239, 0xffff0000, v136
	v_lshlrev_b32_e32 v240, 16, v137
	v_and_b32_e32 v241, 0xffff0000, v137
	v_lshlrev_b32_e32 v242, 16, v138
	v_and_b32_e32 v243, 0xffff0000, v138
	v_lshlrev_b32_e32 v244, 16, v139
	v_and_b32_e32 v245, 0xffff0000, v139
	v_mov_b32_dpp v164, v116 row_half_mirror row_mask:0xf bank_mask:0xf
	v_mov_b32_dpp v165, v117 row_half_mirror row_mask:0xf bank_mask:0xf
	v_mov_b32_dpp v166, v118 row_half_mirror row_mask:0xf bank_mask:0xf
	v_mov_b32_dpp v167, v119 row_half_mirror row_mask:0xf bank_mask:0xf
	v_mov_b32_dpp v178, v120 row_half_mirror row_mask:0xf bank_mask:0xf
	v_mov_b32_dpp v179, v121 row_half_mirror row_mask:0xf bank_mask:0xf
	v_mov_b32_dpp v180, v122 row_half_mirror row_mask:0xf bank_mask:0xf
	v_mov_b32_dpp v181, v123 row_half_mirror row_mask:0xf bank_mask:0xf
	v_mov_b32_dpp v192, v124 row_half_mirror row_mask:0xf bank_mask:0xf
	v_mov_b32_dpp v193, v125 row_half_mirror row_mask:0xf bank_mask:0xf
	v_mov_b32_dpp v194, v126 row_half_mirror row_mask:0xf bank_mask:0xf
	v_mov_b32_dpp v195, v127 row_half_mirror row_mask:0xf bank_mask:0xf
	v_mov_b32_dpp v206, v128 row_half_mirror row_mask:0xf bank_mask:0xf
	v_mov_b32_dpp v207, v129 row_half_mirror row_mask:0xf bank_mask:0xf
	v_mov_b32_dpp v208, v130 row_half_mirror row_mask:0xf bank_mask:0xf
	v_mov_b32_dpp v209, v131 row_half_mirror row_mask:0xf bank_mask:0xf
	v_mul_f32_e32 v90, v168, v168
	v_mul_f32_e32 v91, v182, v182
	v_mul_f32_e32 v92, v196, v196
	v_mul_f32_e32 v93, v210, v210
	v_mul_f32_e32 v94, v224, v224
	v_mul_f32_e32 v95, v238, v238
	v_fmac_f32_e32 v90, v169, v169
	v_fmac_f32_e32 v91, v183, v183
	v_fmac_f32_e32 v92, v197, v197
	v_fmac_f32_e32 v93, v211, v211
	v_fmac_f32_e32 v94, v225, v225
	v_fmac_f32_e32 v95, v239, v239
	v_fmac_f32_e32 v90, v170, v170
	v_fmac_f32_e32 v91, v184, v184
	v_fmac_f32_e32 v92, v198, v198
	v_fmac_f32_e32 v93, v212, v212
	v_fmac_f32_e32 v94, v226, v226
	v_fmac_f32_e32 v95, v240, v240
	v_fmac_f32_e32 v90, v171, v171
	v_fmac_f32_e32 v91, v185, v185
	v_fmac_f32_e32 v92, v199, v199
	v_fmac_f32_e32 v93, v213, v213
	v_fmac_f32_e32 v94, v227, v227
	v_fmac_f32_e32 v95, v241, v241
	v_fmac_f32_e32 v90, v172, v172
	v_fmac_f32_e32 v91, v186, v186
	v_fmac_f32_e32 v92, v200, v200
	v_fmac_f32_e32 v93, v214, v214
	v_fmac_f32_e32 v94, v228, v228
	v_fmac_f32_e32 v95, v242, v242
	v_fmac_f32_e32 v90, v173, v173
	v_fmac_f32_e32 v91, v187, v187
	v_fmac_f32_e32 v92, v201, v201
	v_fmac_f32_e32 v93, v215, v215
	v_fmac_f32_e32 v94, v229, v229
	v_fmac_f32_e32 v95, v243, v243
	v_fmac_f32_e32 v90, v174, v174
	v_fmac_f32_e32 v91, v188, v188
	v_fmac_f32_e32 v92, v202, v202
	v_fmac_f32_e32 v93, v216, v216
	v_fmac_f32_e32 v94, v230, v230
	v_fmac_f32_e32 v95, v244, v244
	v_fmac_f32_e32 v90, v175, v175
	v_fmac_f32_e32 v91, v189, v189
	v_fmac_f32_e32 v92, v203, v203
	v_fmac_f32_e32 v93, v217, v217
	v_fmac_f32_e32 v94, v231, v231
	v_fmac_f32_e32 v95, v245, v245
	v_mov_b32_dpp v164, v164 quad_perm:[3,2,1,0] row_mask:0xf bank_mask:0xf
	v_mov_b32_dpp v165, v165 quad_perm:[3,2,1,0] row_mask:0xf bank_mask:0xf
	v_mov_b32_dpp v166, v166 quad_perm:[3,2,1,0] row_mask:0xf bank_mask:0xf
	v_mov_b32_dpp v167, v167 quad_perm:[3,2,1,0] row_mask:0xf bank_mask:0xf
	v_mov_b32_dpp v178, v178 quad_perm:[3,2,1,0] row_mask:0xf bank_mask:0xf
	v_mov_b32_dpp v179, v179 quad_perm:[3,2,1,0] row_mask:0xf bank_mask:0xf
	v_mov_b32_dpp v180, v180 quad_perm:[3,2,1,0] row_mask:0xf bank_mask:0xf
	v_mov_b32_dpp v181, v181 quad_perm:[3,2,1,0] row_mask:0xf bank_mask:0xf
	v_mov_b32_dpp v192, v192 quad_perm:[3,2,1,0] row_mask:0xf bank_mask:0xf
	v_mov_b32_dpp v193, v193 quad_perm:[3,2,1,0] row_mask:0xf bank_mask:0xf
	v_mov_b32_dpp v194, v194 quad_perm:[3,2,1,0] row_mask:0xf bank_mask:0xf
	v_mov_b32_dpp v195, v195 quad_perm:[3,2,1,0] row_mask:0xf bank_mask:0xf
	v_mov_b32_dpp v206, v206 quad_perm:[3,2,1,0] row_mask:0xf bank_mask:0xf
	v_mov_b32_dpp v207, v207 quad_perm:[3,2,1,0] row_mask:0xf bank_mask:0xf
	v_mov_b32_dpp v208, v208 quad_perm:[3,2,1,0] row_mask:0xf bank_mask:0xf
	v_mov_b32_dpp v209, v209 quad_perm:[3,2,1,0] row_mask:0xf bank_mask:0xf
	v_add_f32_dpp v90, v90, v90 quad_perm:[1,0,3,2] row_mask:0xf bank_mask:0xf
	v_add_f32_dpp v91, v91, v91 quad_perm:[1,0,3,2] row_mask:0xf bank_mask:0xf
	v_add_f32_dpp v92, v92, v92 quad_perm:[1,0,3,2] row_mask:0xf bank_mask:0xf
	v_add_f32_dpp v93, v93, v93 quad_perm:[1,0,3,2] row_mask:0xf bank_mask:0xf
	v_add_f32_dpp v94, v94, v94 quad_perm:[1,0,3,2] row_mask:0xf bank_mask:0xf
	v_add_f32_dpp v95, v95, v95 quad_perm:[1,0,3,2] row_mask:0xf bank_mask:0xf
	v_add_f32_dpp v90, v90, v90 quad_perm:[2,3,0,1] row_mask:0xf bank_mask:0xf
	v_add_f32_dpp v91, v91, v91 quad_perm:[2,3,0,1] row_mask:0xf bank_mask:0xf
	v_add_f32_dpp v92, v92, v92 quad_perm:[2,3,0,1] row_mask:0xf bank_mask:0xf
	v_add_f32_dpp v93, v93, v93 quad_perm:[2,3,0,1] row_mask:0xf bank_mask:0xf
	v_add_f32_dpp v94, v94, v94 quad_perm:[2,3,0,1] row_mask:0xf bank_mask:0xf
	v_add_f32_dpp v95, v95, v95 quad_perm:[2,3,0,1] row_mask:0xf bank_mask:0xf
	v_add_f32_dpp v90, v90, v90 row_half_mirror row_mask:0xf bank_mask:0xf
	v_add_f32_dpp v91, v91, v91 row_half_mirror row_mask:0xf bank_mask:0xf
	v_add_f32_dpp v92, v92, v92 row_half_mirror row_mask:0xf bank_mask:0xf
	v_add_f32_dpp v93, v93, v93 row_half_mirror row_mask:0xf bank_mask:0xf
	v_add_f32_dpp v94, v94, v94 row_half_mirror row_mask:0xf bank_mask:0xf
	v_add_f32_dpp v95, v95, v95 row_half_mirror row_mask:0xf bank_mask:0xf
	v_fmamk_f32 v90, v90, 0x3c800000, v9
	v_fmamk_f32 v91, v91, 0x3c800000, v9
	v_fmamk_f32 v92, v92, 0x3c800000, v9
	v_fmamk_f32 v93, v93, 0x3c800000, v9
	v_fmamk_f32 v94, v94, 0x3c800000, v9
	v_fmamk_f32 v95, v95, 0x3c800000, v9
	v_rsq_f32_e32 v90, v90
	v_rsq_f32_e32 v91, v91
	v_rsq_f32_e32 v92, v92
	v_rsq_f32_e32 v93, v93
	v_rsq_f32_e32 v94, v94
	v_rsq_f32_e32 v95, v95
	v_mul_f32_e32 v168, v168, v58
	v_mul_f32_e32 v169, v169, v59
	v_mul_f32_e32 v170, v170, v60
	v_mul_f32_e32 v171, v171, v61
	v_mul_f32_e32 v172, v172, v62
	v_mul_f32_e32 v173, v173, v63
	v_mul_f32_e32 v174, v174, v64
	v_mul_f32_e32 v175, v175, v65
	v_mul_f32_e32 v182, v182, v74
	v_mul_f32_e32 v183, v183, v75
	v_mul_f32_e32 v184, v184, v76
	v_mul_f32_e32 v185, v185, v77
	v_mul_f32_e32 v186, v186, v78
	v_mul_f32_e32 v187, v187, v79
	v_mul_f32_e32 v188, v188, v80
	v_mul_f32_e32 v189, v189, v81
	v_mul_f32_e32 v196, v196, v58
	v_mul_f32_e32 v197, v197, v59
	v_mul_f32_e32 v198, v198, v60
	v_mul_f32_e32 v199, v199, v61
	v_mul_f32_e32 v200, v200, v62
	v_mul_f32_e32 v201, v201, v63
	v_mul_f32_e32 v202, v202, v64
	v_mul_f32_e32 v203, v203, v65
	v_mul_f32_e32 v210, v210, v74
	v_mul_f32_e32 v211, v211, v75
	v_mul_f32_e32 v212, v212, v76
	v_mul_f32_e32 v213, v213, v77
	v_mul_f32_e32 v214, v214, v78
	v_mul_f32_e32 v215, v215, v79
	v_mul_f32_e32 v216, v216, v80
	v_mul_f32_e32 v217, v217, v81
	v_mul_f32_e32 v224, v224, v100
	v_mul_f32_e32 v225, v225, v101
	v_mul_f32_e32 v226, v226, v102
	v_mul_f32_e32 v227, v227, v103
	v_mul_f32_e32 v228, v228, v104
	v_mul_f32_e32 v229, v229, v105
	v_mul_f32_e32 v230, v230, v106
	v_mul_f32_e32 v231, v231, v107
	v_mul_f32_e32 v238, v238, v108
	v_mul_f32_e32 v239, v239, v109
	v_mul_f32_e32 v240, v240, v110
	v_mul_f32_e32 v241, v241, v111
	v_mul_f32_e32 v242, v242, v112
	v_mul_f32_e32 v243, v243, v113
	v_mul_f32_e32 v244, v244, v114
	v_mul_f32_e32 v245, v245, v115
	v_lshlrev_b32_e32 v176, 16, v164
	v_and_b32_e32 v177, 0xffff0000, v164
	v_lshlrev_b32_e32 v190, 16, v178
	v_and_b32_e32 v191, 0xffff0000, v178
	v_lshlrev_b32_e32 v204, 16, v192
	v_and_b32_e32 v205, 0xffff0000, v192
	v_lshlrev_b32_e32 v218, 16, v206
	v_and_b32_e32 v219, 0xffff0000, v206
	v_fmac_f32_e32 v168, v176, v66
	v_fmac_f32_e32 v169, v177, v67
	v_fmac_f32_e32 v182, v190, v82
	v_fmac_f32_e32 v183, v191, v83
	v_fmac_f32_e32 v196, v204, v66
	v_fmac_f32_e32 v197, v205, v67
	v_fmac_f32_e32 v210, v218, v82
	v_fmac_f32_e32 v211, v219, v83
	v_lshlrev_b32_e32 v176, 16, v165
	v_and_b32_e32 v177, 0xffff0000, v165
	v_lshlrev_b32_e32 v190, 16, v179
	v_and_b32_e32 v191, 0xffff0000, v179
	v_lshlrev_b32_e32 v204, 16, v193
	v_and_b32_e32 v205, 0xffff0000, v193
	v_lshlrev_b32_e32 v218, 16, v207
	v_and_b32_e32 v219, 0xffff0000, v207
	v_fmac_f32_e32 v170, v176, v68
	v_fmac_f32_e32 v171, v177, v69
	v_fmac_f32_e32 v184, v190, v84
	v_fmac_f32_e32 v185, v191, v85
	v_fmac_f32_e32 v198, v204, v68
	v_fmac_f32_e32 v199, v205, v69
	v_fmac_f32_e32 v212, v218, v84
	v_fmac_f32_e32 v213, v219, v85
	v_lshlrev_b32_e32 v176, 16, v166
	v_and_b32_e32 v177, 0xffff0000, v166
	v_lshlrev_b32_e32 v190, 16, v180
	v_and_b32_e32 v191, 0xffff0000, v180
	v_lshlrev_b32_e32 v204, 16, v194
	v_and_b32_e32 v205, 0xffff0000, v194
	v_lshlrev_b32_e32 v218, 16, v208
	v_and_b32_e32 v219, 0xffff0000, v208
	v_fmac_f32_e32 v172, v176, v70
	v_fmac_f32_e32 v173, v177, v71
	v_fmac_f32_e32 v186, v190, v86
	v_fmac_f32_e32 v187, v191, v87
	v_fmac_f32_e32 v200, v204, v70
	v_fmac_f32_e32 v201, v205, v71
	v_fmac_f32_e32 v214, v218, v86
	v_fmac_f32_e32 v215, v219, v87
	v_lshlrev_b32_e32 v176, 16, v167
	v_and_b32_e32 v177, 0xffff0000, v167
	v_lshlrev_b32_e32 v190, 16, v181
	v_and_b32_e32 v191, 0xffff0000, v181
	v_lshlrev_b32_e32 v204, 16, v195
	v_and_b32_e32 v205, 0xffff0000, v195
	v_lshlrev_b32_e32 v218, 16, v209
	v_and_b32_e32 v219, 0xffff0000, v209
	v_fmac_f32_e32 v174, v176, v72
	v_fmac_f32_e32 v175, v177, v73
	v_fmac_f32_e32 v188, v190, v88
	v_fmac_f32_e32 v189, v191, v89
	v_fmac_f32_e32 v202, v204, v72
	v_fmac_f32_e32 v203, v205, v73
	v_fmac_f32_e32 v216, v218, v88
	v_fmac_f32_e32 v217, v219, v89
	v_mul_f32_e32 v168, v168, v90
	v_mul_f32_e32 v169, v169, v90
	v_mul_f32_e32 v170, v170, v90
	v_mul_f32_e32 v171, v171, v90
	v_mul_f32_e32 v172, v172, v90
	v_mul_f32_e32 v173, v173, v90
	v_mul_f32_e32 v174, v174, v90
	v_mul_f32_e32 v175, v175, v90
	v_mul_f32_e32 v182, v182, v91
	v_mul_f32_e32 v183, v183, v91
	v_mul_f32_e32 v184, v184, v91
	v_mul_f32_e32 v185, v185, v91
	v_mul_f32_e32 v186, v186, v91
	v_mul_f32_e32 v187, v187, v91
	v_mul_f32_e32 v188, v188, v91
	v_mul_f32_e32 v189, v189, v91
	v_mul_f32_e32 v196, v196, v92
	v_mul_f32_e32 v197, v197, v92
	v_mul_f32_e32 v198, v198, v92
	v_mul_f32_e32 v199, v199, v92
	v_mul_f32_e32 v200, v200, v92
	v_mul_f32_e32 v201, v201, v92
	v_mul_f32_e32 v202, v202, v92
	v_mul_f32_e32 v203, v203, v92
	v_mul_f32_e32 v210, v210, v93
	v_mul_f32_e32 v211, v211, v93
	v_mul_f32_e32 v212, v212, v93
	v_mul_f32_e32 v213, v213, v93
	v_mul_f32_e32 v214, v214, v93
	v_mul_f32_e32 v215, v215, v93
	v_mul_f32_e32 v216, v216, v93
	v_mul_f32_e32 v217, v217, v93
	v_mul_f32_e32 v224, v224, v94
	v_mul_f32_e32 v225, v225, v94
	v_mul_f32_e32 v226, v226, v94
	v_mul_f32_e32 v227, v227, v94
	v_mul_f32_e32 v228, v228, v94
	v_mul_f32_e32 v229, v229, v94
	v_mul_f32_e32 v230, v230, v94
	v_mul_f32_e32 v231, v231, v94
	v_mul_f32_e32 v238, v238, v95
	v_mul_f32_e32 v239, v239, v95
	v_mul_f32_e32 v240, v240, v95
	v_mul_f32_e32 v241, v241, v95
	v_mul_f32_e32 v242, v242, v95
	v_mul_f32_e32 v243, v243, v95
	v_mul_f32_e32 v244, v244, v95
	v_mul_f32_e32 v245, v245, v95
	v_cvt_pk_bf16_f32 v164, v168, v169
	v_cvt_pk_bf16_f32 v165, v170, v171
	v_cvt_pk_bf16_f32 v166, v172, v173
	v_cvt_pk_bf16_f32 v167, v174, v175
	v_cvt_pk_bf16_f32 v178, v182, v183
	v_cvt_pk_bf16_f32 v179, v184, v185
	v_cvt_pk_bf16_f32 v180, v186, v187
	v_cvt_pk_bf16_f32 v181, v188, v189
	v_cvt_pk_bf16_f32 v192, v196, v197
	v_cvt_pk_bf16_f32 v193, v198, v199
	v_cvt_pk_bf16_f32 v194, v200, v201
	v_cvt_pk_bf16_f32 v195, v202, v203
	v_cvt_pk_bf16_f32 v206, v210, v211
	v_cvt_pk_bf16_f32 v207, v212, v213
	v_cvt_pk_bf16_f32 v208, v214, v215
	v_cvt_pk_bf16_f32 v209, v216, v217
	v_cvt_pk_bf16_f32 v220, v224, v225
	v_cvt_pk_bf16_f32 v221, v226, v227
	v_cvt_pk_bf16_f32 v222, v228, v229
	v_cvt_pk_bf16_f32 v223, v230, v231
	v_cvt_pk_bf16_f32 v234, v238, v239
	v_cvt_pk_bf16_f32 v235, v240, v241
	v_cvt_pk_bf16_f32 v236, v242, v243
	v_cvt_pk_bf16_f32 v237, v244, v245
	s_add_u32 s22, s8, 0x480000
	s_addc_u32 s23, s9, 0
	global_store_dwordx4 v1, v[164:167], s[6:7]
	s_mov_b64 exec, s[44:45]
	global_store_dwordx4 v4, v[178:181], s[8:9]
	s_mov_b64 exec, s[48:49]
	global_store_dwordx4 v4, v[120:123], s[22:23]
	s_mov_b64 exec, s[60:61]
	s_add_u32 s6, s6, 0x400000
	s_addc_u32 s7, s7, 0
	s_add_u32 s8, s8, 0x90000
	s_addc_u32 s9, s9, 0
	s_add_u32 s22, s8, 0x480000
	s_addc_u32 s23, s9, 0
	global_store_dwordx4 v1, v[192:195], s[6:7]
	s_mov_b64 exec, s[44:45]
	global_store_dwordx4 v4, v[206:209], s[8:9]
	s_mov_b64 exec, s[48:49]
	global_store_dwordx4 v4, v[128:131], s[22:23]
	s_mov_b64 exec, s[60:61]
	s_add_u32 s6, s6, 0x400000
	s_addc_u32 s7, s7, 0
	s_add_u32 s8, s8, 0x90000
	s_addc_u32 s9, s9, 0
	s_lshr_b32 s0, s12, 8
	s_and_b32 s1, s12, 0xff
	s_mul_i32 s0, s0, 0x900
	s_add_i32 s0, s0, s1
	s_lshl_b32 s0, s0, 8
	s_add_u32 s8, s34, s0
	s_addc_u32 s9, s35, 0
	s_add_u32 s8, s8, 0xb300000
	s_addc_u32 s9, s9, 0
	s_add_u32 s22, s8, 0x480000
	s_addc_u32 s23, s9, 0
	global_store_dwordx4 v1, v[220:223], s[6:7]
	s_mov_b64 exec, s[44:45]
	global_store_dwordx4 v4, v[234:237], s[8:9]
	s_mov_b64 exec, s[48:49]
	global_store_dwordx4 v4, v[136:139], s[22:23]
	s_mov_b64 exec, s[60:61]
	s_branch .LBB0_1179
qkv_orig_l1:
	v_and_b32_e32 v18, 7, v1
	v_lshlrev_b32_e32 v14, 5, v18
	global_load_dwordx4 v[2:5], v14, s[38:39] offset:256
	global_load_dwordx4 v[6:9], v14, s[40:41] offset:256
	global_load_dwordx4 v[10:13], v14, s[38:39] offset:272
	s_nop 0
	global_load_dwordx4 v[14:17], v14, s[40:41] offset:272
	v_lshlrev_b32_e32 v22, 5, v1
	v_readlane_b32 s48, v250, 19
	v_mov_b32_e32 v19, 0
	v_cmp_gt_u32_e32 vcc, 4, v18
	v_and_b32_e32 v18, 0x60, v22
	v_readlane_b32 s49, v250, 20
	v_mbcnt_lo_u32_b32 v23, -1, 0
	v_and_b32_e32 v21, 63, v1
	v_lshl_add_u64 v[72:73], s[48:49], 0, v[18:19]
	v_readlane_b32 s48, v250, 21
	v_mbcnt_hi_u32_b32 v25, -1, v23
	v_readlane_b32 s49, v250, 22
	s_add_i32 s38, s19, s18
	v_and_b32_e32 v1, 31, v1
	v_lshlrev_b32_e32 v20, 3, v21
	v_cmp_lt_u32_e64 s[0:1], 15, v21
	v_cmp_gt_u32_e64 s[4:5], 32, v21
	v_lshl_add_u64 v[74:75], s[48:49], 0, v[18:19]
	v_lshlrev_b32_e32 v18, 4, v21
	v_and_b32_e32 v21, 64, v25
	s_ashr_i32 s27, s26, 31
	s_ashr_i32 s39, s38, 31
	v_lshlrev_b32_e32 v22, 4, v1
	v_xor_b32_e32 v1, 1, v25
	v_add_u32_e32 v21, 64, v21
	s_lshl_b32 s22, s94, 4
	s_ashr_i32 s3, s12, 31
	s_ashr_i32 s13, s90, 31
	v_cndmask_b32_e64 v70, 1.0, -1.0, vcc
	s_lshl_b64 s[36:37], s[26:27], 11
	v_mov_b32_e32 v23, v19
	v_xor_b32_e32 v30, 2, v25
	s_lshl_b64 s[38:39], s[38:39], 11
	v_cmp_lt_i32_e32 vcc, v1, v21
	s_mov_b64 s[44:45], 0x5900400
	v_xor_b32_e32 v31, 4, v25
	v_lshl_add_u64 v[22:23], s[6:7], 0, v[22:23]
	s_add_u32 s12, s12, s90
	v_cndmask_b32_e32 v1, v25, v1, vcc
	v_cmp_lt_i32_e32 vcc, v30, v21
	v_lshl_add_u64 v[78:79], v[22:23], 0, s[44:45]
	s_addc_u32 s13, s3, s13
	v_cndmask_b32_e32 v22, v25, v30, vcc
	v_cmp_lt_i32_e32 vcc, v31, v21
	s_mov_b64 s[24:25], 0xb780000
	s_mov_b64 s[40:41], 0xb300000
	v_and_b32_e32 v24, 0xf8, v20
	v_lshl_add_u64 v[76:77], s[20:21], 0, v[18:19]
	v_lshl_add_u64 v[26:27], s[54:55], 0, v[18:19]
	v_lshl_add_u64 v[28:29], s[52:53], 0, v[18:19]
	v_lshl_add_u64 v[18:19], s[6:7], 0, v[18:19]
	v_cndmask_b32_e32 v21, v25, v31, vcc
	s_mul_hi_u32 s3, s12, 0xc00
	s_mul_i32 s6, s13, 0xc00
	s_mov_b32 s29, 0
	s_mul_hi_i32 s23, s26, 0xc00
	v_mov_b32_e32 v71, v70
	v_lshl_add_u64 v[80:81], v[26:27], 0, s[24:25]
	v_lshl_add_u64 v[82:83], v[28:29], 0, s[40:41]
	s_mul_i32 s40, s12, 0xc00
	v_lshl_add_u64 v[84:85], v[18:19], 0, s[8:9]
	v_lshlrev_b32_e32 v1, 2, v1
	v_lshlrev_b32_e32 v120, 2, v22
	v_lshlrev_b32_e32 v121, 2, v21
	s_lshl_b64 s[44:45], s[12:13], 11
	s_add_i32 s41, s3, s6
	s_movk_i32 s27, 0x7ff
	v_lshlrev_b32_e32 v122, 1, v20
	v_lshlrev_b32_e32 v123, 1, v24
	s_mov_b32 s33, 0xffff0000
	v_mov_b32_e32 v124, 0x358637bd
	s_mov_b32 s49, 0xf800000
	v_mov_b32_e32 v125, 0x260
	s_mov_b32 s48, 0x3e38aa3b
	s_movk_i32 s56, 0x7fff
	s_waitcnt vmcnt(3)
	v_mov_b32_e32 v86, v2
	v_mov_b32_e32 v87, v4
	v_mov_b32_e32 v4, v3
	s_waitcnt vmcnt(2)
	v_mov_b32_e32 v2, v6
	v_mov_b32_e32 v3, v8
	v_mov_b32_e32 v8, v7
	s_waitcnt vmcnt(1)
	v_mov_b32_e32 v6, v10
	v_mov_b32_e32 v7, v12
	v_mov_b32_e32 v12, v11
	s_waitcnt vmcnt(0)
	v_mov_b32_e32 v10, v14
	v_mov_b32_e32 v11, v16
	v_mov_b32_e32 v16, v15
	v_mov_b64_e32 v[14:15], v[76:77]
	s_branch .LBB0_1158
